# relaxed first-iteration waits + sc1 on gemm1/ffn-up/down/merge epilogue stores
# baseline (speedup 1.0000x reference)
; __device__ __forceinline__ unsigned cvt_pk_bf16(float lo, float hi) { unsigned r; asm volatile("v_cvt_pk_bf16_f32 %0, %1, %2" : "=v"(r) : "v"(lo), "v"(hi)); return r; }
;     __device__ __forceinline__ void operator()(const f32x4 (&acc)[2][2][4][2], const Unit& u, int wr, int wc, int fr, int fq) const {
;     ...
;         for (int ai = 0; ai < 2; ++ai)
; #pragma unroll
;             for (int m = 0; m < 4; ++m) { bf16_t* rowp = base + (size_t)(row0 + ai * HALF + m * 16) * ld + col0;
; #pragma unroll
;                 for (int bj = 0; bj < 2; ++bj) { f32x4 v0 = acc[ai][bj][m][0] + bv[bj][0], v1 = acc[ai][bj][m][1] + bv[bj][1];
;                     if (sig) {
; #pragma unroll
;                         for (int j = 0; j < 4; ++j) { v0[j] = __builtin_amdgcn_rcpf(1.0f + __expf(-v0[j])); v1[j] = __builtin_amdgcn_rcpf(1.0f + __expf(-v1[j])); } }
;                     u32x4 w; w.x = cvt_pk_bf16(v0[0], v0[1]); w.y = cvt_pk_bf16(v0[2], v0[3]); w.z = cvt_pk_bf16(v1[0], v1[1]); w.w = cvt_pk_bf16(v1[2], v1[3]);
;                     *(u32x4*)(rowp + bj * HALF) = w; } }
.LBB0_41:
	v_lshl_or_b32 v140, s14, 8, v144
	v_lshl_add_u32 v146, s13, 8, v142
	v_ashrrev_i32_e32 v141, 31, v140
	v_ashrrev_i32_e32 v147, 31, v146
	v_lshl_add_u64 v[148:149], v[140:141], 1, s[28:29]
	v_lshlrev_b64 v[140:141], 11, v[146:147]
	v_lshl_add_u64 v[140:141], v[148:149], 0, v[140:141]
	v_pk_add_f32 v[128:129], v[128:129], 0 op_sel_hi:[1,0]
	v_pk_add_f32 v[126:127], v[126:127], 0 op_sel_hi:[1,0]
	v_pk_add_f32 v[150:151], v[124:125], 0 op_sel_hi:[1,0]
	v_pk_add_f32 v[124:125], v[122:123], 0 op_sel_hi:[1,0]
	v_cvt_pk_bf16_f32 v122, v126, v127
	v_cvt_pk_bf16_f32 v123, v128, v129
	v_pk_add_f32 v[118:119], v[118:119], 0 op_sel_hi:[1,0]
	v_cvt_pk_bf16_f32 v124, v124, v125
	v_cvt_pk_bf16_f32 v125, v150, v151
	global_store_dwordx4 v[140:141], v[122:125], off sc1
	v_pk_add_f32 v[120:121], v[120:121], 0 op_sel_hi:[1,0]
	v_pk_add_f32 v[114:115], v[114:115], 0 op_sel_hi:[1,0]
	v_pk_add_f32 v[122:123], v[112:113], 0 op_sel_hi:[1,0]
	v_pk_add_f32 v[112:113], v[110:111], 0 op_sel_hi:[1,0]
	v_cvt_pk_bf16_f32 v110, v118, v119
	v_cvt_pk_bf16_f32 v111, v120, v121
	v_pk_add_f32 v[102:103], v[102:103], 0 op_sel_hi:[1,0]
	v_cvt_pk_bf16_f32 v112, v112, v113
	v_cvt_pk_bf16_f32 v113, v122, v123
	global_store_dwordx4 v[140:141], v[110:113], off offset:256 sc1
	v_pk_add_f32 v[104:105], v[104:105], 0 op_sel_hi:[1,0]
	v_pk_add_f32 v[98:99], v[98:99], 0 op_sel_hi:[1,0]
	v_or_b32_e32 v110, 16, v146
	v_ashrrev_i32_e32 v111, 31, v110
	v_lshlrev_b64 v[110:111], 11, v[110:111]
	v_lshl_add_u64 v[110:111], v[148:149], 0, v[110:111]
	v_pk_add_f32 v[112:113], v[116:117], 0 op_sel_hi:[1,0]
	v_pk_add_f32 v[116:117], v[108:109], 0 op_sel_hi:[1,0]
	v_pk_add_f32 v[108:109], v[106:107], 0 op_sel_hi:[1,0]
	v_cvt_pk_bf16_f32 v106, v114, v115
	v_cvt_pk_bf16_f32 v107, v112, v113
	v_pk_add_f32 v[86:87], v[86:87], 0 op_sel_hi:[1,0]
	v_cvt_pk_bf16_f32 v108, v108, v109
	v_cvt_pk_bf16_f32 v109, v116, v117
	global_store_dwordx4 v[110:111], v[106:109], off sc1
	v_pk_add_f32 v[88:89], v[88:89], 0 op_sel_hi:[1,0]
	v_pk_add_f32 v[82:83], v[82:83], 0 op_sel_hi:[1,0]
	v_pk_add_f32 v[106:107], v[96:97], 0 op_sel_hi:[1,0]
	v_pk_add_f32 v[96:97], v[94:95], 0 op_sel_hi:[1,0]
	v_cvt_pk_bf16_f32 v94, v102, v103
	v_cvt_pk_bf16_f32 v95, v104, v105
	v_pk_add_f32 v[72:73], v[72:73], 0 op_sel_hi:[1,0]
	v_cvt_pk_bf16_f32 v96, v96, v97
	v_cvt_pk_bf16_f32 v97, v106, v107
	global_store_dwordx4 v[110:111], v[94:97], off offset:256 sc1
	v_pk_add_f32 v[70:71], v[70:71], 0 op_sel_hi:[1,0]
	v_pk_add_f32 v[62:63], v[62:63], 0 op_sel_hi:[1,0]
	v_or_b32_e32 v94, 32, v146
	v_ashrrev_i32_e32 v95, 31, v94
	v_lshlrev_b64 v[94:95], 11, v[94:95]
	v_lshl_add_u64 v[94:95], v[148:149], 0, v[94:95]
	v_pk_add_f32 v[96:97], v[100:101], 0 op_sel_hi:[1,0]
	v_pk_add_f32 v[100:101], v[92:93], 0 op_sel_hi:[1,0]
	v_pk_add_f32 v[92:93], v[90:91], 0 op_sel_hi:[1,0]
	v_cvt_pk_bf16_f32 v90, v98, v99
	v_cvt_pk_bf16_f32 v91, v96, v97
	s_mov_b32 s13, 0x40000
	v_cvt_pk_bf16_f32 v92, v92, v93
	v_cvt_pk_bf16_f32 v93, v100, v101
	global_store_dwordx4 v[94:95], v[90:93], off sc1
	v_pk_add_f32 v[64:65], v[64:65], 0 op_sel_hi:[1,0]
	s_mov_b64 s[14:15], 0x40000
	v_pk_add_f32 v[90:91], v[80:81], 0 op_sel_hi:[1,0]
	v_pk_add_f32 v[80:81], v[78:79], 0 op_sel_hi:[1,0]
	v_cvt_pk_bf16_f32 v78, v86, v87
	v_cvt_pk_bf16_f32 v79, v88, v89
	v_pk_add_f32 v[56:57], v[56:57], 0 op_sel_hi:[1,0]
	v_cvt_pk_bf16_f32 v80, v80, v81
	v_cvt_pk_bf16_f32 v81, v90, v91
	global_store_dwordx4 v[94:95], v[78:81], off offset:256 sc1
	v_pk_add_f32 v[54:55], v[54:55], 0 op_sel_hi:[1,0]
	v_pk_add_f32 v[50:51], v[50:51], 0 op_sel_hi:[1,0]
	v_or_b32_e32 v78, 48, v146
	v_ashrrev_i32_e32 v79, 31, v78
	v_lshlrev_b64 v[78:79], 11, v[78:79]
	v_lshl_add_u64 v[78:79], v[148:149], 0, v[78:79]
	v_pk_add_f32 v[80:81], v[84:85], 0 op_sel_hi:[1,0]
	v_pk_add_f32 v[84:85], v[76:77], 0 op_sel_hi:[1,0]
	v_pk_add_f32 v[76:77], v[74:75], 0 op_sel_hi:[1,0]
	v_cvt_pk_bf16_f32 v74, v82, v83
	v_cvt_pk_bf16_f32 v75, v80, v81
	v_pk_add_f32 v[40:41], v[40:41], 0 op_sel_hi:[1,0]
	v_cvt_pk_bf16_f32 v76, v76, v77
	v_cvt_pk_bf16_f32 v77, v84, v85
	global_store_dwordx4 v[78:79], v[74:77], off sc1
; __device__ __forceinline__ unsigned cvt_pk_bf16(float lo, float hi) { unsigned r; asm volatile("v_cvt_pk_bf16_f32 %0, %1, %2" : "=v"(r) : "v"(lo), "v"(hi)); return r; }
; #define PG8_BAR __builtin_amdgcn_s_barrier()
; template <class Epi>
; __device__ __forceinline__ void gemm_phase(LAS unsigned char* lds, const Gemm g, const Order& S, const Epi& E) {
;     ...
;         if (!has_next) break;
;         if constexpr (!Epi::KEEP_ACC) {
; #pragma unroll
;         for (int a = 0; a < 2; ++a)
; #pragma unroll
;             for (int b = 0; b < 2; ++b)
; #pragma unroll
;                 for (int m = 0; m < 4; ++m)
; #pragma unroll
;                     for (int n = 0; n < 2; ++n) acc[a][b][m][n] = (f32x4){0.f, 0.f, 0.f, 0.f};
;         }
;         cur = nxt; cA = nA; cB = nB; ++ui;
;         if (wr == 1) PG8_BAR;
;     __device__ __forceinline__ void operator()(const f32x4 (&acc)[2][2][4][2], const Unit& u, int wr, int wc, int fr, int fq) const {
;     ...
;         for (int ai = 0; ai < 2; ++ai)
; #pragma unroll
;             for (int m = 0; m < 4; ++m) { bf16_t* rowp = base + (size_t)(row0 + ai * HALF + m * 16) * ld + col0;
; #pragma unroll
;                 for (int bj = 0; bj < 2; ++bj) { f32x4 v0 = acc[ai][bj][m][0] + bv[bj][0], v1 = acc[ai][bj][m][1] + bv[bj][1];
;                     if (sig) {
; #pragma unroll
;                         for (int j = 0; j < 4; ++j) { v0[j] = __builtin_amdgcn_rcpf(1.0f + __expf(-v0[j])); v1[j] = __builtin_amdgcn_rcpf(1.0f + __expf(-v1[j])); } }
;                     u32x4 w; w.x = cvt_pk_bf16(v0[0], v0[1]); w.y = cvt_pk_bf16(v0[2], v0[3]); w.z = cvt_pk_bf16(v1[0], v1[1]); w.w = cvt_pk_bf16(v1[2], v1[3]);
;                     *(u32x4*)(rowp + bj * HALF) = w; } }
	v_pk_add_f32 v[38:39], v[38:39], 0 op_sel_hi:[1,0]
	v_pk_add_f32 v[34:35], v[34:35], 0 op_sel_hi:[1,0]
	v_pk_add_f32 v[74:75], v[68:69], 0 op_sel_hi:[1,0]
	v_pk_add_f32 v[68:69], v[66:67], 0 op_sel_hi:[1,0]
	v_cvt_pk_bf16_f32 v66, v70, v71
	v_cvt_pk_bf16_f32 v67, v72, v73
	v_pk_add_f32 v[24:25], v[24:25], 0 op_sel_hi:[1,0]
	v_cvt_pk_bf16_f32 v68, v68, v69
	v_cvt_pk_bf16_f32 v69, v74, v75
	global_store_dwordx4 v[78:79], v[66:69], off offset:256 sc1
	v_pk_add_f32 v[22:23], v[22:23], 0 op_sel_hi:[1,0]
	v_pk_add_f32 v[18:19], v[18:19], 0 op_sel_hi:[1,0]
	v_pk_add_f32 v[68:69], v[60:61], 0 op_sel_hi:[1,0]
	v_pk_add_f32 v[60:61], v[58:59], 0 op_sel_hi:[1,0]
	v_cvt_pk_bf16_f32 v58, v62, v63
	v_add_co_u32_e32 v62, vcc, s13, v140
	v_cvt_pk_bf16_f32 v59, v64, v65
	v_cvt_pk_bf16_f32 v60, v60, v61
	v_cvt_pk_bf16_f32 v61, v68, v69
	v_lshl_add_u64 v[66:67], v[140:141], 0, s[14:15]
	s_nop 0
	v_addc_co_u32_e32 v63, vcc, 0, v141, vcc
	global_store_dwordx4 v[62:63], v[58:61], off sc1
	s_mov_b32 s13, 0x48000
	s_mov_b64 s[14:15], 0x48000
	v_pk_add_f32 v[58:59], v[48:49], 0 op_sel_hi:[1,0]
	v_pk_add_f32 v[48:49], v[46:47], 0 op_sel_hi:[1,0]
	v_cvt_pk_bf16_f32 v46, v54, v55
	v_cvt_pk_bf16_f32 v47, v56, v57
	v_readlane_b32 s16, v255, 27
	v_cvt_pk_bf16_f32 v48, v48, v49
	v_cvt_pk_bf16_f32 v49, v58, v59
	global_store_dwordx4 v[66:67], v[46:49], off offset:256 sc1
	v_readlane_b32 s17, v255, 28
	v_pk_add_f32 v[8:9], v[8:9], 0 op_sel_hi:[1,0]
	v_pk_add_f32 v[48:49], v[52:53], 0 op_sel_hi:[1,0]
	v_pk_add_f32 v[52:53], v[44:45], 0 op_sel_hi:[1,0]
	v_pk_add_f32 v[44:45], v[42:43], 0 op_sel_hi:[1,0]
	v_cvt_pk_bf16_f32 v42, v50, v51
	v_cvt_pk_bf16_f32 v43, v48, v49
	v_add_co_u32_e32 v48, vcc, s13, v140
	v_cvt_pk_bf16_f32 v44, v44, v45
	v_cvt_pk_bf16_f32 v45, v52, v53
	v_lshl_add_u64 v[46:47], v[140:141], 0, s[14:15]
	s_nop 0
	v_addc_co_u32_e32 v49, vcc, 0, v141, vcc
	global_store_dwordx4 v[48:49], v[42:45], off sc1
	s_mov_b32 s13, 0x50000
	s_mov_b64 s[14:15], 0x50000
	v_pk_add_f32 v[42:43], v[32:33], 0 op_sel_hi:[1,0]
	v_pk_add_f32 v[32:33], v[30:31], 0 op_sel_hi:[1,0]
	v_cvt_pk_bf16_f32 v30, v38, v39
	v_cvt_pk_bf16_f32 v31, v40, v41
	v_pk_add_f32 v[6:7], v[6:7], 0 op_sel_hi:[1,0]
	v_cvt_pk_bf16_f32 v32, v32, v33
	v_cvt_pk_bf16_f32 v33, v42, v43
	global_store_dwordx4 v[46:47], v[30:33], off offset:256 sc1
	s_nop 1
	v_pk_add_f32 v[32:33], v[36:37], 0 op_sel_hi:[1,0]
	v_pk_add_f32 v[36:37], v[28:29], 0 op_sel_hi:[1,0]
	v_pk_add_f32 v[28:29], v[26:27], 0 op_sel_hi:[1,0]
	v_cvt_pk_bf16_f32 v26, v34, v35
	v_cvt_pk_bf16_f32 v27, v32, v33
	v_add_co_u32_e32 v32, vcc, s13, v140
	v_cvt_pk_bf16_f32 v28, v28, v29
	v_cvt_pk_bf16_f32 v29, v36, v37
	v_lshl_add_u64 v[30:31], v[140:141], 0, s[14:15]
	s_nop 0
	v_addc_co_u32_e32 v33, vcc, 0, v141, vcc
	global_store_dwordx4 v[32:33], v[26:29], off sc1
	s_mov_b32 s13, 0x58000
	s_mov_b64 s[14:15], 0x58000
	v_pk_add_f32 v[26:27], v[16:17], 0 op_sel_hi:[1,0]
	v_pk_add_f32 v[16:17], v[14:15], 0 op_sel_hi:[1,0]
	v_cvt_pk_bf16_f32 v14, v22, v23
	v_cvt_pk_bf16_f32 v15, v24, v25
	s_nop 0
	v_cvt_pk_bf16_f32 v16, v16, v17
	v_cvt_pk_bf16_f32 v17, v26, v27
	global_store_dwordx4 v[30:31], v[14:17], off offset:256 sc1
	s_nop 1
	v_pk_add_f32 v[16:17], v[20:21], 0 op_sel_hi:[1,0]
	v_pk_add_f32 v[20:21], v[12:13], 0 op_sel_hi:[1,0]
	v_pk_add_f32 v[12:13], v[10:11], 0 op_sel_hi:[1,0]
	v_cvt_pk_bf16_f32 v10, v18, v19
	v_cvt_pk_bf16_f32 v11, v16, v17
	v_add_co_u32_e32 v16, vcc, s13, v140
	v_lshl_add_u64 v[14:15], v[140:141], 0, s[14:15]
	s_nop 0
	v_addc_co_u32_e32 v17, vcc, 0, v141, vcc
	v_cvt_pk_bf16_f32 v12, v12, v13
	v_cvt_pk_bf16_f32 v13, v20, v21
	global_store_dwordx4 v[16:17], v[10:13], off sc1
	s_and_b64 vcc, exec, s[36:37]
	s_mov_b64 s[36:37], -1
	v_pk_add_f32 v[10:11], v[4:5], 0 op_sel_hi:[1,0]
	v_pk_add_f32 v[4:5], v[2:3], 0 op_sel_hi:[1,0]
	v_cvt_pk_bf16_f32 v2, v6, v7
	v_cvt_pk_bf16_f32 v3, v8, v9
	s_nop 0
	v_cvt_pk_bf16_f32 v4, v4, v5
	v_cvt_pk_bf16_f32 v5, v10, v11
	global_store_dwordx4 v[14:15], v[2:5], off offset:256 sc1
	s_cbranch_vccnz .LBB0_26
	s_andn2_b64 vcc, exec, s[30:31]
	s_cbranch_vccnz .LBB0_25
	s_barrier
	s_branch .LBB0_25

; #define LAS __attribute__((address_space(3)))
; __device__ __forceinline__ u32x4 pack8(const float (&f)[8]) { u32x4 w; w.x = cvt_pk_bf16(f[0], f[1]); w.y = cvt_pk_bf16(f[2], f[3]); w.z = cvt_pk_bf16(f[4], f[5]); w.w = cvt_pk_bf16(f[6], f[7]); return w; }
; __device__ __forceinline__ float dpp_row_shr1(float x) { return __int_as_float(__builtin_amdgcn_update_dpp(0, __float_as_int(x), 0x111, 0xf, 0xf, false)); }
;     __device__ __forceinline__ void operator()(const f32x4 (&acc)[2][2][4][2], const Unit& u, int wr, int wc, int fr, int fq) const {
;     ...
;             for (int m = 0; m < 4; ++m) {
;                 const int B = 2 * ai + wr;
;                 float g8[8], u8[8], q15[8], q14[8], o[8];
; #pragma unroll
;                 for (int j = 0; j < 4; ++j) { g8[j] = acc[ai][0][m][0][j]; g8[4 + j] = acc[ai][0][m][1][j]; u8[j] = acc[ai][1][m][0][j]; u8[4 + j] = acc[ai][1][m][1][j]; }
;                 if (m == 0) {
;                     if (B > 0) { const LAS float* p = XG + ((B - 1) * 2) * 128 + chl; const f32x4 r0a = *(const LAS f32x4*)p, r0b = *(const LAS f32x4*)(p + 4), r1a = *(const LAS f32x4*)(p + 128), r1b = *(const LAS f32x4*)(p + 132);
; #pragma unroll
;                         for (int j = 0; j < 4; ++j) { q14[j] = r0a[j]; q14[4 + j] = r0b[j]; q15[j] = r1a[j]; q15[4 + j] = r1b[j]; } }
;                     else {
; #pragma unroll
;                         for (int j = 0; j < 8; ++j) { q14[j] = 0.f; q15[j] = 0.f; } }
;                     float p1a[8], p2a[8];
; #pragma unroll
;                     for (int e = 0; e < 8; ++e) { const float s1 = dpp_row_shr1(g8[e]), s2 = dpp_row_shr2(g8[e]);
;                         p1a[e] = (fr >= 1) ? s1 : q15[e]; p2a[e] = (fr >= 2) ? s2 : ((fr == 1) ? q15[e] : q14[e]); }
; #pragma unroll
;                     for (int e = 0; e < 8; e += 2) { const f32x2 gt = (f32x2){w0[e], w0[e + 1]} * (f32x2){p2a[e], p2a[e + 1]} + (f32x2){w1[e], w1[e + 1]} * (f32x2){p1a[e], p1a[e + 1]} + (f32x2){w2[e], w2[e + 1]} * (f32x2){g8[e], g8[e + 1]} + (f32x2){bb[e], bb[e + 1]};
;                         const f32x2 r = gelu_tanh_mul2(gt, (f32x2){u8[e], u8[e + 1]}); o[e] = r.x; o[e + 1] = r.y; }
;     ...
;                 const int rloc = 128 * ai + 64 * wr + 16 * m + fr;
;                 if (!(B == 0 && m == 0 && fr < 2)) *(u32x4*)(ACT + (size_t)(u.pm * BM + rloc) * FF + chg) = pack8(o);
.LBB0_82:
	v_mov_b32_e32 v211, 0
	v_mov_b32_e32 v213, 0
	v_mov_b32_e32 v212, 0
	v_mov_b32_e32 v214, 0
	v_mov_b32_e32 v215, 0
	v_mov_b32_e32 v217, 0
	v_mov_b32_e32 v216, 0
	v_mov_b32_e32 v218, 0
	v_mov_b32_e32 v219, 0
	v_mov_b32_e32 v221, 0
	v_mov_b32_e32 v220, 0
	v_mov_b32_e32 v222, 0
	v_mov_b32_e32 v223, 0
	v_mov_b32_e32 v225, 0
	v_mov_b32_e32 v224, 0
	v_mov_b32_e32 v226, 0
	v_lshl_add_u32 v210, s30, 8, v204
	v_mov_b32_dpp v211, v150 row_shr:1 row_mask:0xf bank_mask:0xf
	v_mov_b32_dpp v213, v150 row_shr:2 row_mask:0xf bank_mask:0xf
	v_mov_b32_dpp v212, v151 row_shr:1 row_mask:0xf bank_mask:0xf
	v_mov_b32_dpp v214, v151 row_shr:2 row_mask:0xf bank_mask:0xf
	v_mov_b32_dpp v215, v152 row_shr:1 row_mask:0xf bank_mask:0xf
	v_mov_b32_dpp v217, v152 row_shr:2 row_mask:0xf bank_mask:0xf
	v_mov_b32_dpp v216, v153 row_shr:1 row_mask:0xf bank_mask:0xf
	v_mov_b32_dpp v218, v153 row_shr:2 row_mask:0xf bank_mask:0xf
	v_mov_b32_dpp v219, v146 row_shr:1 row_mask:0xf bank_mask:0xf
	v_mov_b32_dpp v221, v146 row_shr:2 row_mask:0xf bank_mask:0xf
	v_mov_b32_dpp v220, v147 row_shr:1 row_mask:0xf bank_mask:0xf
	v_mov_b32_dpp v222, v147 row_shr:2 row_mask:0xf bank_mask:0xf
	v_mov_b32_dpp v223, v148 row_shr:1 row_mask:0xf bank_mask:0xf
	v_mov_b32_dpp v225, v148 row_shr:2 row_mask:0xf bank_mask:0xf
	v_mov_b32_dpp v224, v149 row_shr:1 row_mask:0xf bank_mask:0xf
	v_mov_b32_dpp v226, v149 row_shr:2 row_mask:0xf bank_mask:0xf
	s_and_saveexec_b64 s[8:9], s[58:59]
	s_xor_b64 s[30:31], exec, s[8:9]
	s_cbranch_execz .LBB0_84
	s_waitcnt lgkmcnt(0)
	v_cndmask_b32_e64 v170, v170, v174, s[42:43]
	v_cndmask_b32_e64 v171, v171, v175, s[42:43]
	v_cndmask_b32_e64 v164, v164, v168, s[42:43]
	v_cndmask_b32_e64 v165, v165, v169, s[42:43]
	v_cndmask_b32_e64 v162, v162, v166, s[42:43]
	v_cndmask_b32_e64 v163, v163, v167, s[42:43]
	v_cndmask_b32_e64 v170, v170, v221, s[38:39]
	v_cndmask_b32_e64 v171, v171, v222, s[38:39]
	v_cndmask_b32_e64 v164, v164, v217, s[38:39]
	v_cndmask_b32_e64 v165, v165, v218, s[38:39]
	v_cndmask_b32_e64 v162, v162, v213, s[38:39]
	v_cndmask_b32_e64 v163, v163, v214, s[38:39]
	s_waitcnt vmcnt(0)
	v_pk_mul_f32 v[170:171], v[66:67], v[170:171]
	v_cndmask_b32_e64 v174, v219, v174, s[40:41]
	v_cndmask_b32_e64 v175, v220, v175, s[40:41]
	v_pk_mul_f32 v[164:165], v[92:93], v[164:165]
	v_cndmask_b32_e64 v168, v215, v168, s[40:41]
	v_cndmask_b32_e64 v169, v216, v169, s[40:41]
	v_pk_mul_f32 v[162:163], v[90:91], v[162:163]
	v_cndmask_b32_e64 v166, v211, v166, s[40:41]
	v_cndmask_b32_e64 v167, v212, v167, s[40:41]
	v_pk_fma_f32 v[170:171], v[70:71], v[174:175], v[170:171]
	v_pk_fma_f32 v[164:165], v[96:97], v[168:169], v[164:165]
	v_pk_fma_f32 v[162:163], v[94:95], v[166:167], v[162:163]
	v_cndmask_b32_e64 v172, v172, v176, s[42:43]
	v_cndmask_b32_e64 v173, v173, v177, s[42:43]
	v_pk_fma_f32 v[170:171], v[146:147], v[74:75], v[170:171]
	v_pk_fma_f32 v[164:165], v[152:153], v[100:101], v[164:165]
	v_pk_fma_f32 v[162:163], v[150:151], v[98:99], v[162:163]
	v_cndmask_b32_e64 v172, v172, v225, s[38:39]
	v_cndmask_b32_e64 v173, v173, v226, s[38:39]
	v_pk_add_f32 v[170:171], v[78:79], v[170:171]
	v_pk_add_f32 v[164:165], v[104:105], v[164:165]
	v_pk_add_f32 v[162:163], v[102:103], v[162:163]
	v_pk_mul_f32 v[172:173], v[68:69], v[172:173]
	v_cndmask_b32_e64 v176, v223, v176, s[40:41]
	v_cndmask_b32_e64 v177, v224, v177, s[40:41]
	v_pk_mul_f32 v[174:175], v[170:171], v[170:171]
	v_pk_mul_f32 v[168:169], v[164:165], v[164:165]
	v_pk_mul_f32 v[166:167], v[162:163], v[162:163]
	v_pk_fma_f32 v[172:173], v[72:73], v[176:177], v[172:173]
	v_pk_fma_f32 v[174:175], v[174:175], s[78:79], 1.0 op_sel_hi:[1,0,0]
	v_pk_fma_f32 v[168:169], v[168:169], s[78:79], 1.0 op_sel_hi:[1,0,0]
	v_pk_fma_f32 v[166:167], v[166:167], s[78:79], 1.0 op_sel_hi:[1,0,0]
	v_pk_fma_f32 v[172:173], v[148:149], v[76:77], v[172:173]
	v_pk_mul_f32 v[174:175], v[170:171], v[174:175]
	v_pk_mul_f32 v[168:169], v[164:165], v[168:169]
	v_pk_mul_f32 v[166:167], v[162:163], v[166:167]
	v_pk_add_f32 v[172:173], v[80:81], v[172:173]
	v_pk_mul_f32 v[174:175], v[174:175], s[24:25] op_sel_hi:[1,0]
	v_pk_mul_f32 v[168:169], v[168:169], s[24:25] op_sel_hi:[1,0]
	v_pk_mul_f32 v[166:167], v[166:167], s[24:25] op_sel_hi:[1,0]
	v_pk_mul_f32 v[176:177], v[172:173], v[172:173]
	v_exp_f32_e32 v174, v174
	v_exp_f32_e32 v175, v175
	v_exp_f32_e32 v168, v168
	v_exp_f32_e32 v169, v169
	v_exp_f32_e32 v166, v166
	v_exp_f32_e32 v167, v167
	v_pk_fma_f32 v[176:177], v[176:177], s[78:79], 1.0 op_sel_hi:[1,0,0]
	v_pk_add_f32 v[174:175], v[174:175], 1.0 op_sel_hi:[1,0]
	v_pk_mul_f32 v[176:177], v[172:173], v[176:177]
	v_pk_add_f32 v[168:169], v[168:169], 1.0 op_sel_hi:[1,0]
	v_pk_mul_f32 v[176:177], v[176:177], s[24:25] op_sel_hi:[1,0]
	v_pk_add_f32 v[166:167], v[166:167], 1.0 op_sel_hi:[1,0]
	v_exp_f32_e32 v176, v176
	v_exp_f32_e32 v177, v177
	v_rcp_f32_e32 v174, v174
	v_rcp_f32_e32 v175, v175
	v_rcp_f32_e32 v168, v168
	v_rcp_f32_e32 v169, v169
	v_rcp_f32_e32 v166, v166
	v_rcp_f32_e32 v167, v167
	v_pk_add_f32 v[176:177], v[176:177], 1.0 op_sel_hi:[1,0]
	v_pk_mul_f32 v[170:171], v[170:171], v[174:175]
	v_rcp_f32_e32 v176, v176
	v_rcp_f32_e32 v177, v177
	v_pk_mul_f32 v[164:165], v[164:165], v[168:169]
	v_pk_mul_f32 v[162:163], v[162:163], v[166:167]
	v_readlane_b32 s8, v253, 57
	v_pk_mul_f32 v[158:159], v[158:159], v[170:171]
	v_pk_mul_f32 v[156:157], v[156:157], v[164:165]
	v_pk_mul_f32 v[154:155], v[154:155], v[162:163]
	v_readlane_b32 s9, v253, 58
	v_cvt_pk_bf16_f32 v154, v154, v155
	v_cvt_pk_bf16_f32 v155, v156, v157
	v_cvt_pk_bf16_f32 v156, v158, v159
	s_movk_i32 s7, 0x1600
	v_pk_mul_f32 v[172:173], v[172:173], v[176:177]
	v_mov_b64_e32 v[158:159], s[8:9]
	v_mad_i64_i32 v[158:159], s[8:9], v210, s7, v[158:159]
	v_lshl_add_u64 v[158:159], v[192:193], 1, v[158:159]
	v_pk_mul_f32 v[160:161], v[160:161], v[172:173]
	s_nop 0
	v_cvt_pk_bf16_f32 v157, v160, v161
	global_store_dwordx4 v[158:159], v[154:157], off sc1
; __device__ __forceinline__ float dpp_row_shr1(float x) { return __int_as_float(__builtin_amdgcn_update_dpp(0, __float_as_int(x), 0x111, 0xf, 0xf, false)); }
; __device__ __forceinline__ float dpp_row_shr2(float x) { return __int_as_float(__builtin_amdgcn_update_dpp(0, __float_as_int(x), 0x112, 0xf, 0xf, false)); }
; __device__ __forceinline__ float dpp_row_ror1(float x) { return __int_as_float(__builtin_amdgcn_update_dpp(0, __float_as_int(x), 0x121, 0xf, 0xf, false)); }
; __device__ __forceinline__ float dpp_row_ror2(float x) { return __int_as_float(__builtin_amdgcn_update_dpp(0, __float_as_int(x), 0x122, 0xf, 0xf, false)); }
;     __device__ __forceinline__ void operator()(const f32x4 (&acc)[2][2][4][2], const Unit& u, int wr, int wc, int fr, int fq) const {
;     ...
;                 } else {
;                     float p1a[8], p2a[8];
; #pragma unroll
;                     for (int e = 0; e < 8; ++e) { const float pv = (e < 4) ? acc[ai][0][m - 1][0][e & 3] : acc[ai][0][m - 1][1][e & 3];
;                         const float s1 = dpp_row_shr1(g8[e]), s2 = dpp_row_shr2(g8[e]), r1 = dpp_row_ror1(pv), r2 = dpp_row_ror2(pv);
;                         p1a[e] = (fr >= 1) ? s1 : r1; p2a[e] = (fr >= 2) ? s2 : r2; }
; #pragma unroll
;                     for (int e = 0; e < 8; e += 2) { const f32x2 gt = (f32x2){w0[e], w0[e + 1]} * (f32x2){p2a[e], p2a[e + 1]} + (f32x2){w1[e], w1[e + 1]} * (f32x2){p1a[e], p1a[e + 1]} + (f32x2){w2[e], w2[e + 1]} * (f32x2){g8[e], g8[e + 1]} + (f32x2){bb[e], bb[e + 1]};
;                         const f32x2 r = gelu_tanh_mul2(gt, (f32x2){u8[e], u8[e + 1]}); o[e] = r.x; o[e + 1] = r.y; }
.LBB0_84:
	s_andn2_saveexec_b64 s[30:31], s[30:31]
	s_or_b64 exec, exec, s[30:31]
	v_mov_b32_e32 v154, v195
	v_mov_b32_e32 v155, v195
	v_mov_b32_e32 v156, v195
	v_mov_b32_e32 v157, v195
	v_mov_b32_dpp v154, v134 row_shr:1 row_mask:0xf bank_mask:0xf
	v_mov_b32_dpp v155, v134 row_shr:2 row_mask:0xf bank_mask:0xf
	v_mov_b32_dpp v156, v150 row_ror:1 row_mask:0xf bank_mask:0xf
	v_mov_b32_dpp v157, v150 row_ror:2 row_mask:0xf bank_mask:0xf
	v_cndmask_b32_e64 v150, v154, v156, s[40:41]
	v_cndmask_b32_e64 v154, v157, v155, s[38:39]
	v_mov_b32_e32 v155, v195
	v_mov_b32_e32 v156, v195
	v_mov_b32_e32 v157, v195
	v_mov_b32_e32 v158, v195
	v_mov_b32_dpp v155, v135 row_shr:1 row_mask:0xf bank_mask:0xf
	v_mov_b32_dpp v156, v135 row_shr:2 row_mask:0xf bank_mask:0xf
	v_mov_b32_dpp v157, v151 row_ror:1 row_mask:0xf bank_mask:0xf
	v_mov_b32_dpp v158, v151 row_ror:2 row_mask:0xf bank_mask:0xf
	v_cndmask_b32_e64 v151, v155, v157, s[40:41]
	v_cndmask_b32_e64 v155, v158, v156, s[38:39]
	v_mov_b32_e32 v156, v195
	v_mov_b32_e32 v157, v195
	v_mov_b32_e32 v158, v195
	v_mov_b32_e32 v159, v195
	v_mov_b32_dpp v156, v136 row_shr:1 row_mask:0xf bank_mask:0xf
	v_mov_b32_dpp v157, v136 row_shr:2 row_mask:0xf bank_mask:0xf
	v_mov_b32_dpp v158, v152 row_ror:1 row_mask:0xf bank_mask:0xf
	v_mov_b32_dpp v159, v152 row_ror:2 row_mask:0xf bank_mask:0xf
	v_cndmask_b32_e64 v152, v156, v158, s[40:41]
	v_cndmask_b32_e64 v156, v159, v157, s[38:39]
	v_mov_b32_e32 v157, v195
	v_mov_b32_e32 v158, v195
	v_mov_b32_e32 v159, v195
	v_mov_b32_e32 v160, v195
	v_mov_b32_dpp v157, v137 row_shr:1 row_mask:0xf bank_mask:0xf
	v_mov_b32_dpp v158, v137 row_shr:2 row_mask:0xf bank_mask:0xf
	v_mov_b32_dpp v159, v153 row_ror:1 row_mask:0xf bank_mask:0xf
	v_mov_b32_dpp v160, v153 row_ror:2 row_mask:0xf bank_mask:0xf
	v_cndmask_b32_e64 v153, v157, v159, s[40:41]
	v_cndmask_b32_e64 v157, v160, v158, s[38:39]
	s_waitcnt vmcnt(0)
	v_pk_mul_f32 v[154:155], v[90:91], v[154:155]
	v_pk_mul_f32 v[156:157], v[92:93], v[156:157]
	v_pk_fma_f32 v[150:151], v[94:95], v[150:151], v[154:155]
	v_pk_fma_f32 v[152:153], v[96:97], v[152:153], v[156:157]
	v_pk_fma_f32 v[150:151], v[134:135], v[98:99], v[150:151]
	v_pk_fma_f32 v[152:153], v[136:137], v[100:101], v[152:153]
	v_pk_add_f32 v[150:151], v[102:103], v[150:151]
	v_pk_add_f32 v[152:153], v[104:105], v[152:153]
	v_pk_mul_f32 v[154:155], v[150:151], v[150:151]
	v_pk_mul_f32 v[156:157], v[152:153], v[152:153]
	v_pk_fma_f32 v[154:155], v[154:155], s[78:79], 1.0 op_sel_hi:[1,0,0]
	v_pk_fma_f32 v[156:157], v[156:157], s[78:79], 1.0 op_sel_hi:[1,0,0]
	v_pk_mul_f32 v[154:155], v[150:151], v[154:155]
	v_pk_mul_f32 v[156:157], v[152:153], v[156:157]
	v_pk_mul_f32 v[154:155], v[154:155], s[24:25] op_sel_hi:[1,0]
	v_pk_mul_f32 v[156:157], v[156:157], s[24:25] op_sel_hi:[1,0]
	v_exp_f32_e32 v154, v154
	v_exp_f32_e32 v155, v155
	v_exp_f32_e32 v156, v156
	v_exp_f32_e32 v157, v157
	v_mov_b32_e32 v158, v195
	v_mov_b32_e32 v159, v195
	v_mov_b32_e32 v160, v195
	v_mov_b32_e32 v161, v195
	v_mov_b32_dpp v158, v130 row_shr:1 row_mask:0xf bank_mask:0xf
	v_mov_b32_dpp v159, v130 row_shr:2 row_mask:0xf bank_mask:0xf
	v_mov_b32_dpp v160, v146 row_ror:1 row_mask:0xf bank_mask:0xf
	v_mov_b32_dpp v161, v146 row_ror:2 row_mask:0xf bank_mask:0xf
	v_cndmask_b32_e64 v146, v158, v160, s[40:41]
	v_cndmask_b32_e64 v158, v161, v159, s[38:39]
	v_mov_b32_e32 v159, v195
	v_mov_b32_e32 v160, v195
	v_mov_b32_e32 v161, v195
	s_waitcnt lgkmcnt(3)
	v_mov_b32_e32 v162, v195
	v_pk_add_f32 v[154:155], v[154:155], 1.0 op_sel_hi:[1,0]
	v_mov_b32_dpp v159, v131 row_shr:1 row_mask:0xf bank_mask:0xf
	v_mov_b32_dpp v160, v131 row_shr:2 row_mask:0xf bank_mask:0xf
	v_mov_b32_dpp v161, v147 row_ror:1 row_mask:0xf bank_mask:0xf
	v_mov_b32_dpp v162, v147 row_ror:2 row_mask:0xf bank_mask:0xf
	v_rcp_f32_e32 v154, v154
	v_rcp_f32_e32 v155, v155
	v_pk_add_f32 v[156:157], v[156:157], 1.0 op_sel_hi:[1,0]
	v_cndmask_b32_e64 v147, v159, v161, s[40:41]
	v_cndmask_b32_e64 v159, v162, v160, s[38:39]
	v_mov_b32_e32 v160, v195
	v_mov_b32_e32 v161, v195
	v_mov_b32_e32 v162, v195
	v_mov_b32_e32 v163, v195
	v_rcp_f32_e32 v156, v156
	v_rcp_f32_e32 v157, v157
	v_mov_b32_dpp v160, v132 row_shr:1 row_mask:0xf bank_mask:0xf
	v_mov_b32_dpp v161, v132 row_shr:2 row_mask:0xf bank_mask:0xf
	v_mov_b32_dpp v162, v148 row_ror:1 row_mask:0xf bank_mask:0xf
	v_mov_b32_dpp v163, v148 row_ror:2 row_mask:0xf bank_mask:0xf
	v_cndmask_b32_e64 v148, v160, v162, s[40:41]
	v_cndmask_b32_e64 v160, v163, v161, s[38:39]
	v_mov_b32_e32 v161, v195
	v_mov_b32_e32 v162, v195
	v_mov_b32_e32 v163, v195
	v_mov_b32_e32 v164, v195
	v_mov_b32_dpp v161, v133 row_shr:1 row_mask:0xf bank_mask:0xf
	v_mov_b32_dpp v162, v133 row_shr:2 row_mask:0xf bank_mask:0xf
	v_mov_b32_dpp v163, v149 row_ror:1 row_mask:0xf bank_mask:0xf
	v_mov_b32_dpp v164, v149 row_ror:2 row_mask:0xf bank_mask:0xf
	v_pk_mul_f32 v[150:151], v[150:151], v[154:155]
	v_cndmask_b32_e64 v149, v161, v163, s[40:41]
	v_cndmask_b32_e64 v161, v164, v162, s[38:39]
	v_pk_mul_f32 v[142:143], v[142:143], v[150:151]
	v_pk_mul_f32 v[150:151], v[152:153], v[156:157]
	v_pk_mul_f32 v[152:153], v[66:67], v[158:159]
	v_pk_mul_f32 v[154:155], v[68:69], v[160:161]
	v_pk_fma_f32 v[146:147], v[70:71], v[146:147], v[152:153]
	v_pk_fma_f32 v[148:149], v[72:73], v[148:149], v[154:155]
	v_pk_fma_f32 v[146:147], v[130:131], v[74:75], v[146:147]
	v_pk_fma_f32 v[148:149], v[132:133], v[76:77], v[148:149]
	v_pk_add_f32 v[146:147], v[78:79], v[146:147]
	v_pk_add_f32 v[148:149], v[80:81], v[148:149]
	v_pk_mul_f32 v[152:153], v[146:147], v[146:147]
	v_pk_mul_f32 v[154:155], v[148:149], v[148:149]
	v_pk_fma_f32 v[152:153], v[152:153], s[78:79], 1.0 op_sel_hi:[1,0,0]
; __device__ __forceinline__ u32x4 pack8(const float (&f)[8]) { u32x4 w; w.x = cvt_pk_bf16(f[0], f[1]); w.y = cvt_pk_bf16(f[2], f[3]); w.z = cvt_pk_bf16(f[4], f[5]); w.w = cvt_pk_bf16(f[6], f[7]); return w; }
; __device__ __forceinline__ float dpp_row_shr1(float x) { return __int_as_float(__builtin_amdgcn_update_dpp(0, __float_as_int(x), 0x111, 0xf, 0xf, false)); }
; __device__ __forceinline__ float dpp_row_shr2(float x) { return __int_as_float(__builtin_amdgcn_update_dpp(0, __float_as_int(x), 0x112, 0xf, 0xf, false)); }
; __device__ __forceinline__ float dpp_row_ror1(float x) { return __int_as_float(__builtin_amdgcn_update_dpp(0, __float_as_int(x), 0x121, 0xf, 0xf, false)); }
; __device__ __forceinline__ float dpp_row_ror2(float x) { return __int_as_float(__builtin_amdgcn_update_dpp(0, __float_as_int(x), 0x122, 0xf, 0xf, false)); }
;     __device__ __forceinline__ void operator()(const f32x4 (&acc)[2][2][4][2], const Unit& u, int wr, int wc, int fr, int fq) const {
;     ...
;                 } else {
;                     float p1a[8], p2a[8];
; #pragma unroll
;                     for (int e = 0; e < 8; ++e) { const float pv = (e < 4) ? acc[ai][0][m - 1][0][e & 3] : acc[ai][0][m - 1][1][e & 3];
;                         const float s1 = dpp_row_shr1(g8[e]), s2 = dpp_row_shr2(g8[e]), r1 = dpp_row_ror1(pv), r2 = dpp_row_ror2(pv);
;                         p1a[e] = (fr >= 1) ? s1 : r1; p2a[e] = (fr >= 2) ? s2 : r2; }
; #pragma unroll
;                     for (int e = 0; e < 8; e += 2) { const f32x2 gt = (f32x2){w0[e], w0[e + 1]} * (f32x2){p2a[e], p2a[e + 1]} + (f32x2){w1[e], w1[e + 1]} * (f32x2){p1a[e], p1a[e + 1]} + (f32x2){w2[e], w2[e + 1]} * (f32x2){g8[e], g8[e + 1]} + (f32x2){bb[e], bb[e + 1]};
;                         const f32x2 r = gelu_tanh_mul2(gt, (f32x2){u8[e], u8[e + 1]}); o[e] = r.x; o[e + 1] = r.y; }
;                 }
;                 const int rloc = 128 * ai + 64 * wr + 16 * m + fr;
;                 if (!(B == 0 && m == 0 && fr < 2)) *(u32x4*)(ACT + (size_t)(u.pm * BM + rloc) * FF + chg) = pack8(o);
	v_pk_fma_f32 v[154:155], v[154:155], s[78:79], 1.0 op_sel_hi:[1,0,0]
	v_pk_mul_f32 v[152:153], v[146:147], v[152:153]
	v_pk_mul_f32 v[154:155], v[148:149], v[154:155]
	v_pk_mul_f32 v[152:153], v[152:153], s[24:25] op_sel_hi:[1,0]
	v_pk_mul_f32 v[154:155], v[154:155], s[24:25] op_sel_hi:[1,0]
	v_exp_f32_e32 v152, v152
	v_exp_f32_e32 v153, v153
	v_exp_f32_e32 v154, v154
	v_exp_f32_e32 v155, v155
	v_readlane_b32 s8, v253, 57
	v_pk_add_f32 v[152:153], v[152:153], 1.0 op_sel_hi:[1,0]
	v_pk_mul_f32 v[144:145], v[144:145], v[150:151]
	v_rcp_f32_e32 v152, v152
	v_rcp_f32_e32 v153, v153
	v_pk_add_f32 v[154:155], v[154:155], 1.0 op_sel_hi:[1,0]
	v_readlane_b32 s9, v253, 58
	v_rcp_f32_e32 v154, v154
	v_rcp_f32_e32 v155, v155
	v_pk_mul_f32 v[146:147], v[146:147], v[152:153]
	v_cvt_pk_bf16_f32 v142, v142, v143
	v_cvt_pk_bf16_f32 v143, v144, v145
	s_movk_i32 s7, 0x1600
	v_pk_mul_f32 v[138:139], v[138:139], v[146:147]
	v_pk_mul_f32 v[146:147], v[148:149], v[154:155]
	v_cvt_pk_bf16_f32 v144, v138, v139
	v_or_b32_e32 v138, 16, v210
	v_pk_mul_f32 v[140:141], v[140:141], v[146:147]
	v_mov_b32_e32 v148, v195
	v_cvt_pk_bf16_f32 v145, v140, v141
	v_mov_b64_e32 v[140:141], s[8:9]
	v_mad_i64_i32 v[146:147], s[8:9], v138, s7, v[140:141]
	v_lshlrev_b64 v[138:139], 1, v[192:193]
	v_lshl_add_u64 v[146:147], v[146:147], 0, v[138:139]
	global_store_dwordx4 v[146:147], v[142:145], off sc1
	v_mov_b32_e32 v146, v195
	v_mov_b32_e32 v147, v195
	v_mov_b32_e32 v142, v195
	v_mov_b32_e32 v143, v195
	v_mov_b32_e32 v144, v195
	v_mov_b32_e32 v145, v195
	v_mov_b32_dpp v142, v118 row_shr:1 row_mask:0xf bank_mask:0xf
	v_mov_b32_dpp v143, v118 row_shr:2 row_mask:0xf bank_mask:0xf
	v_mov_b32_dpp v144, v134 row_ror:1 row_mask:0xf bank_mask:0xf
	v_mov_b32_dpp v145, v134 row_ror:2 row_mask:0xf bank_mask:0xf
	v_cndmask_b32_e64 v134, v142, v144, s[40:41]
	v_cndmask_b32_e64 v142, v145, v143, s[38:39]
	v_mov_b32_e32 v143, v195
	v_mov_b32_e32 v144, v195
	v_mov_b32_e32 v145, v195
	v_mov_b32_dpp v143, v119 row_shr:1 row_mask:0xf bank_mask:0xf
	v_mov_b32_dpp v144, v119 row_shr:2 row_mask:0xf bank_mask:0xf
	v_mov_b32_dpp v145, v135 row_ror:1 row_mask:0xf bank_mask:0xf
	v_mov_b32_dpp v146, v135 row_ror:2 row_mask:0xf bank_mask:0xf
	v_cndmask_b32_e64 v135, v143, v145, s[40:41]
	v_cndmask_b32_e64 v143, v146, v144, s[38:39]
	v_mov_b32_e32 v144, v195
	v_mov_b32_e32 v145, v195
	v_mov_b32_e32 v146, v195
	v_mov_b32_dpp v144, v120 row_shr:1 row_mask:0xf bank_mask:0xf
	v_mov_b32_dpp v145, v120 row_shr:2 row_mask:0xf bank_mask:0xf
	v_mov_b32_dpp v146, v136 row_ror:1 row_mask:0xf bank_mask:0xf
	v_mov_b32_dpp v147, v136 row_ror:2 row_mask:0xf bank_mask:0xf
	v_cndmask_b32_e64 v136, v144, v146, s[40:41]
	v_cndmask_b32_e64 v144, v147, v145, s[38:39]
	v_mov_b32_e32 v145, v195
	v_mov_b32_e32 v146, v195
	v_mov_b32_e32 v147, v195
	v_mov_b32_dpp v145, v121 row_shr:1 row_mask:0xf bank_mask:0xf
	v_mov_b32_dpp v146, v121 row_shr:2 row_mask:0xf bank_mask:0xf
	v_mov_b32_dpp v147, v137 row_ror:1 row_mask:0xf bank_mask:0xf
	v_mov_b32_dpp v148, v137 row_ror:2 row_mask:0xf bank_mask:0xf
	v_cndmask_b32_e64 v137, v145, v147, s[40:41]
	v_cndmask_b32_e64 v145, v148, v146, s[38:39]
	v_pk_mul_f32 v[142:143], v[90:91], v[142:143]
	v_pk_mul_f32 v[144:145], v[92:93], v[144:145]
	v_pk_fma_f32 v[134:135], v[94:95], v[134:135], v[142:143]
	v_pk_fma_f32 v[136:137], v[96:97], v[136:137], v[144:145]
	v_pk_fma_f32 v[134:135], v[118:119], v[98:99], v[134:135]
	v_pk_fma_f32 v[136:137], v[120:121], v[100:101], v[136:137]
	v_pk_add_f32 v[134:135], v[102:103], v[134:135]
	v_pk_add_f32 v[136:137], v[104:105], v[136:137]
	v_pk_mul_f32 v[142:143], v[134:135], v[134:135]
	v_pk_mul_f32 v[144:145], v[136:137], v[136:137]
	v_pk_fma_f32 v[142:143], v[142:143], s[78:79], 1.0 op_sel_hi:[1,0,0]
	v_pk_fma_f32 v[144:145], v[144:145], s[78:79], 1.0 op_sel_hi:[1,0,0]
	v_pk_mul_f32 v[142:143], v[134:135], v[142:143]
	v_pk_mul_f32 v[144:145], v[136:137], v[144:145]
	v_pk_mul_f32 v[142:143], v[142:143], s[24:25] op_sel_hi:[1,0]
	v_pk_mul_f32 v[144:145], v[144:145], s[24:25] op_sel_hi:[1,0]
	v_exp_f32_e32 v142, v142
	v_exp_f32_e32 v143, v143
	v_exp_f32_e32 v144, v144
	v_exp_f32_e32 v145, v145
	v_mov_b32_e32 v146, v195
	v_mov_b32_e32 v147, v195
	v_mov_b32_e32 v148, v195
	v_mov_b32_e32 v149, v195
	v_mov_b32_dpp v146, v114 row_shr:1 row_mask:0xf bank_mask:0xf
	v_mov_b32_dpp v147, v114 row_shr:2 row_mask:0xf bank_mask:0xf
	v_mov_b32_dpp v148, v130 row_ror:1 row_mask:0xf bank_mask:0xf
	v_mov_b32_dpp v149, v130 row_ror:2 row_mask:0xf bank_mask:0xf
	v_cndmask_b32_e64 v130, v146, v148, s[40:41]
	v_cndmask_b32_e64 v146, v149, v147, s[38:39]
	v_mov_b32_e32 v147, v195
	v_mov_b32_e32 v148, v195
	v_mov_b32_e32 v149, v195
	v_mov_b32_e32 v150, v195
	v_pk_add_f32 v[142:143], v[142:143], 1.0 op_sel_hi:[1,0]
	v_mov_b32_dpp v147, v115 row_shr:1 row_mask:0xf bank_mask:0xf
	v_mov_b32_dpp v148, v115 row_shr:2 row_mask:0xf bank_mask:0xf
	v_mov_b32_dpp v149, v131 row_ror:1 row_mask:0xf bank_mask:0xf
	v_mov_b32_dpp v150, v131 row_ror:2 row_mask:0xf bank_mask:0xf
	v_rcp_f32_e32 v142, v142
	v_rcp_f32_e32 v143, v143
	v_pk_add_f32 v[144:145], v[144:145], 1.0 op_sel_hi:[1,0]
	v_cndmask_b32_e64 v131, v147, v149, s[40:41]
	v_cndmask_b32_e64 v147, v150, v148, s[38:39]
	v_mov_b32_e32 v148, v195
	v_mov_b32_e32 v149, v195
	v_mov_b32_e32 v150, v195
	v_mov_b32_e32 v151, v195
	v_rcp_f32_e32 v144, v144
	v_rcp_f32_e32 v145, v145
	v_mov_b32_dpp v148, v116 row_shr:1 row_mask:0xf bank_mask:0xf
	v_mov_b32_dpp v149, v116 row_shr:2 row_mask:0xf bank_mask:0xf
	v_mov_b32_dpp v150, v132 row_ror:1 row_mask:0xf bank_mask:0xf
	v_mov_b32_dpp v151, v132 row_ror:2 row_mask:0xf bank_mask:0xf
	v_cndmask_b32_e64 v132, v148, v150, s[40:41]
; __device__ __forceinline__ u32x4 pack8(const float (&f)[8]) { u32x4 w; w.x = cvt_pk_bf16(f[0], f[1]); w.y = cvt_pk_bf16(f[2], f[3]); w.z = cvt_pk_bf16(f[4], f[5]); w.w = cvt_pk_bf16(f[6], f[7]); return w; }
; __device__ __forceinline__ float dpp_row_shr1(float x) { return __int_as_float(__builtin_amdgcn_update_dpp(0, __float_as_int(x), 0x111, 0xf, 0xf, false)); }
; __device__ __forceinline__ float dpp_row_shr2(float x) { return __int_as_float(__builtin_amdgcn_update_dpp(0, __float_as_int(x), 0x112, 0xf, 0xf, false)); }
; __device__ __forceinline__ float dpp_row_ror1(float x) { return __int_as_float(__builtin_amdgcn_update_dpp(0, __float_as_int(x), 0x121, 0xf, 0xf, false)); }
; __device__ __forceinline__ float dpp_row_ror2(float x) { return __int_as_float(__builtin_amdgcn_update_dpp(0, __float_as_int(x), 0x122, 0xf, 0xf, false)); }
;     __device__ __forceinline__ void operator()(const f32x4 (&acc)[2][2][4][2], const Unit& u, int wr, int wc, int fr, int fq) const {
;     ...
;                     float p1a[8], p2a[8];
; #pragma unroll
;                     for (int e = 0; e < 8; ++e) { const float pv = (e < 4) ? acc[ai][0][m - 1][0][e & 3] : acc[ai][0][m - 1][1][e & 3];
;                         const float s1 = dpp_row_shr1(g8[e]), s2 = dpp_row_shr2(g8[e]), r1 = dpp_row_ror1(pv), r2 = dpp_row_ror2(pv);
;                         p1a[e] = (fr >= 1) ? s1 : r1; p2a[e] = (fr >= 2) ? s2 : r2; }
; #pragma unroll
;                     for (int e = 0; e < 8; e += 2) { const f32x2 gt = (f32x2){w0[e], w0[e + 1]} * (f32x2){p2a[e], p2a[e + 1]} + (f32x2){w1[e], w1[e + 1]} * (f32x2){p1a[e], p1a[e + 1]} + (f32x2){w2[e], w2[e + 1]} * (f32x2){g8[e], g8[e + 1]} + (f32x2){bb[e], bb[e + 1]};
;                         const f32x2 r = gelu_tanh_mul2(gt, (f32x2){u8[e], u8[e + 1]}); o[e] = r.x; o[e + 1] = r.y; }
;                 }
;                 const int rloc = 128 * ai + 64 * wr + 16 * m + fr;
;                 if (!(B == 0 && m == 0 && fr < 2)) *(u32x4*)(ACT + (size_t)(u.pm * BM + rloc) * FF + chg) = pack8(o);
	v_cndmask_b32_e64 v148, v151, v149, s[38:39]
	v_mov_b32_e32 v149, v195
	v_mov_b32_e32 v150, v195
	v_mov_b32_e32 v151, v195
	v_mov_b32_e32 v152, v195
	v_mov_b32_dpp v149, v117 row_shr:1 row_mask:0xf bank_mask:0xf
	v_mov_b32_dpp v150, v117 row_shr:2 row_mask:0xf bank_mask:0xf
	v_mov_b32_dpp v151, v133 row_ror:1 row_mask:0xf bank_mask:0xf
	v_mov_b32_dpp v152, v133 row_ror:2 row_mask:0xf bank_mask:0xf
	v_pk_mul_f32 v[134:135], v[134:135], v[142:143]
	v_cndmask_b32_e64 v133, v149, v151, s[40:41]
	v_cndmask_b32_e64 v149, v152, v150, s[38:39]
	v_pk_mul_f32 v[126:127], v[126:127], v[134:135]
	v_pk_mul_f32 v[134:135], v[136:137], v[144:145]
	v_pk_mul_f32 v[136:137], v[66:67], v[146:147]
	v_pk_mul_f32 v[142:143], v[68:69], v[148:149]
	v_pk_fma_f32 v[130:131], v[70:71], v[130:131], v[136:137]
	v_pk_fma_f32 v[132:133], v[72:73], v[132:133], v[142:143]
	v_pk_fma_f32 v[130:131], v[114:115], v[74:75], v[130:131]
	v_pk_fma_f32 v[132:133], v[116:117], v[76:77], v[132:133]
	v_pk_add_f32 v[130:131], v[78:79], v[130:131]
	v_pk_add_f32 v[132:133], v[80:81], v[132:133]
	v_pk_mul_f32 v[136:137], v[130:131], v[130:131]
	v_pk_mul_f32 v[142:143], v[132:133], v[132:133]
	v_pk_fma_f32 v[136:137], v[136:137], s[78:79], 1.0 op_sel_hi:[1,0,0]
	v_pk_fma_f32 v[142:143], v[142:143], s[78:79], 1.0 op_sel_hi:[1,0,0]
	v_pk_mul_f32 v[136:137], v[130:131], v[136:137]
	v_pk_mul_f32 v[142:143], v[132:133], v[142:143]
	v_pk_mul_f32 v[136:137], v[136:137], s[24:25] op_sel_hi:[1,0]
	v_pk_mul_f32 v[142:143], v[142:143], s[24:25] op_sel_hi:[1,0]
	v_exp_f32_e32 v136, v136
	v_exp_f32_e32 v137, v137
	v_exp_f32_e32 v142, v142
	v_exp_f32_e32 v143, v143
	v_pk_mul_f32 v[128:129], v[128:129], v[134:135]
	v_pk_add_f32 v[136:137], v[136:137], 1.0 op_sel_hi:[1,0]
	s_movk_i32 s10, 0x1600
	v_rcp_f32_e32 v136, v136
	v_rcp_f32_e32 v137, v137
	v_pk_add_f32 v[142:143], v[142:143], 1.0 op_sel_hi:[1,0]
	s_andn2_b64 vcc, exec, s[62:63]
	v_rcp_f32_e32 v142, v142
	v_rcp_f32_e32 v143, v143
	v_pk_mul_f32 v[130:131], v[130:131], v[136:137]
	s_nop 0
	v_pk_mul_f32 v[130:131], v[122:123], v[130:131]
	v_pk_mul_f32 v[122:123], v[132:133], v[142:143]
	s_nop 0
	v_pk_mul_f32 v[132:133], v[124:125], v[122:123]
	v_cvt_pk_bf16_f32 v122, v126, v127
	v_or_b32_e32 v126, 32, v210
	v_mad_i64_i32 v[126:127], s[8:9], v126, s7, v[140:141]
	v_cvt_pk_bf16_f32 v123, v128, v129
	v_cvt_pk_bf16_f32 v124, v130, v131
	v_cvt_pk_bf16_f32 v125, v132, v133
	v_lshl_add_u64 v[126:127], v[126:127], 0, v[138:139]
	global_store_dwordx4 v[126:127], v[122:125], off sc1
	v_mov_b32_e32 v126, v195
	v_mov_b32_e32 v127, v195
	v_mov_b32_e32 v122, v195
	v_mov_b32_e32 v123, v195
	v_mov_b32_e32 v124, v195
	v_mov_b32_e32 v125, v195
	v_mov_b32_dpp v122, v110 row_shr:1 row_mask:0xf bank_mask:0xf
	v_mov_b32_dpp v123, v110 row_shr:2 row_mask:0xf bank_mask:0xf
	v_mov_b32_dpp v124, v118 row_ror:1 row_mask:0xf bank_mask:0xf
	v_mov_b32_dpp v125, v118 row_ror:2 row_mask:0xf bank_mask:0xf
	v_cndmask_b32_e64 v118, v122, v124, s[40:41]
	v_cndmask_b32_e64 v122, v125, v123, s[38:39]
	v_mov_b32_e32 v123, v195
	v_mov_b32_e32 v124, v195
	v_mov_b32_e32 v125, v195
	v_mov_b32_dpp v123, v111 row_shr:1 row_mask:0xf bank_mask:0xf
	v_mov_b32_dpp v124, v111 row_shr:2 row_mask:0xf bank_mask:0xf
	v_mov_b32_dpp v125, v119 row_ror:1 row_mask:0xf bank_mask:0xf
	v_mov_b32_dpp v126, v119 row_ror:2 row_mask:0xf bank_mask:0xf
	v_cndmask_b32_e64 v119, v123, v125, s[40:41]
	v_cndmask_b32_e64 v123, v126, v124, s[38:39]
	v_mov_b32_e32 v124, v195
	v_mov_b32_e32 v125, v195
	v_mov_b32_e32 v126, v195
	v_mov_b32_dpp v124, v112 row_shr:1 row_mask:0xf bank_mask:0xf
	v_mov_b32_dpp v125, v112 row_shr:2 row_mask:0xf bank_mask:0xf
	v_mov_b32_dpp v126, v120 row_ror:1 row_mask:0xf bank_mask:0xf
	v_mov_b32_dpp v127, v120 row_ror:2 row_mask:0xf bank_mask:0xf
	v_cndmask_b32_e64 v120, v124, v126, s[40:41]
	v_cndmask_b32_e64 v124, v127, v125, s[38:39]
	v_mov_b32_e32 v125, v195
	v_mov_b32_e32 v126, v195
	v_mov_b32_e32 v127, v195
	v_mov_b32_e32 v128, v195
	v_mov_b32_dpp v125, v113 row_shr:1 row_mask:0xf bank_mask:0xf
	v_mov_b32_dpp v126, v113 row_shr:2 row_mask:0xf bank_mask:0xf
	v_mov_b32_dpp v127, v121 row_ror:1 row_mask:0xf bank_mask:0xf
	v_mov_b32_dpp v128, v121 row_ror:2 row_mask:0xf bank_mask:0xf
	v_cndmask_b32_e64 v121, v125, v127, s[40:41]
	v_cndmask_b32_e64 v125, v128, v126, s[38:39]
	v_pk_mul_f32 v[122:123], v[90:91], v[122:123]
	v_mov_b32_e32 v126, v195
	v_pk_fma_f32 v[118:119], v[94:95], v[118:119], v[122:123]
	v_pk_mul_f32 v[122:123], v[92:93], v[124:125]
	v_pk_fma_f32 v[110:111], v[110:111], v[98:99], v[118:119]
	v_pk_fma_f32 v[120:121], v[96:97], v[120:121], v[122:123]
	v_pk_add_f32 v[110:111], v[102:103], v[110:111]
	v_pk_fma_f32 v[112:113], v[112:113], v[100:101], v[120:121]
	v_pk_mul_f32 v[118:119], v[110:111], v[110:111]
	v_pk_add_f32 v[112:113], v[104:105], v[112:113]
	v_pk_fma_f32 v[118:119], v[118:119], s[78:79], 1.0 op_sel_hi:[1,0,0]
	v_pk_mul_f32 v[120:121], v[112:113], v[112:113]
	v_pk_mul_f32 v[118:119], v[110:111], v[118:119]
	v_pk_fma_f32 v[120:121], v[120:121], s[78:79], 1.0 op_sel_hi:[1,0,0]
	v_pk_mul_f32 v[118:119], v[118:119], s[24:25] op_sel_hi:[1,0]
	v_pk_mul_f32 v[120:121], v[112:113], v[120:121]
	v_exp_f32_e32 v118, v118
	v_exp_f32_e32 v119, v119
	v_pk_mul_f32 v[120:121], v[120:121], s[24:25] op_sel_hi:[1,0]
	v_mov_b32_e32 v127, v195
	v_exp_f32_e32 v120, v120
	v_exp_f32_e32 v121, v121
	v_mov_b32_e32 v128, v195
	v_mov_b32_e32 v129, v195
	v_mov_b32_dpp v126, v106 row_shr:1 row_mask:0xf bank_mask:0xf
	v_mov_b32_dpp v127, v106 row_shr:2 row_mask:0xf bank_mask:0xf
	v_mov_b32_dpp v128, v114 row_ror:1 row_mask:0xf bank_mask:0xf
	v_mov_b32_dpp v129, v114 row_ror:2 row_mask:0xf bank_mask:0xf
; #define LAS __attribute__((address_space(3)))
; __device__ __forceinline__ u32x4 pack8(const float (&f)[8]) { u32x4 w; w.x = cvt_pk_bf16(f[0], f[1]); w.y = cvt_pk_bf16(f[2], f[3]); w.z = cvt_pk_bf16(f[4], f[5]); w.w = cvt_pk_bf16(f[6], f[7]); return w; }
;     __device__ __forceinline__ void operator()(const f32x4 (&acc)[2][2][4][2], const Unit& u, int wr, int wc, int fr, int fq) const {
;     ...
;                     if (B > 0) { const LAS float* p = XG + ((B - 1) * 2) * 128 + chl; const f32x4 r0a = *(const LAS f32x4*)p, r0b = *(const LAS f32x4*)(p + 4), r1a = *(const LAS f32x4*)(p + 128), r1b = *(const LAS f32x4*)(p + 132);
; #pragma unroll
;                         for (int j = 0; j < 4; ++j) { q14[j] = r0a[j]; q14[4 + j] = r0b[j]; q15[j] = r1a[j]; q15[4 + j] = r1b[j]; } }
;                     else {
; #pragma unroll
;                         for (int j = 0; j < 8; ++j) { q14[j] = 0.f; q15[j] = 0.f; } }
;                     float p1a[8], p2a[8];
; #pragma unroll
;                     for (int e = 0; e < 8; ++e) { const float s1 = dpp_row_shr1(g8[e]), s2 = dpp_row_shr2(g8[e]);
;                         p1a[e] = (fr >= 1) ? s1 : q15[e]; p2a[e] = (fr >= 2) ? s2 : ((fr == 1) ? q15[e] : q14[e]); }
;     ...
;                     float p1a[8], p2a[8];
; #pragma unroll
;                     for (int e = 0; e < 8; ++e) { const float pv = (e < 4) ? acc[ai][0][m - 1][0][e & 3] : acc[ai][0][m - 1][1][e & 3];
;                         const float s1 = dpp_row_shr1(g8[e]), s2 = dpp_row_shr2(g8[e]), r1 = dpp_row_ror1(pv), r2 = dpp_row_ror2(pv);
;                         p1a[e] = (fr >= 1) ? s1 : r1; p2a[e] = (fr >= 2) ? s2 : r2; }
; #pragma unroll
;                     for (int e = 0; e < 8; e += 2) { const f32x2 gt = (f32x2){w0[e], w0[e + 1]} * (f32x2){p2a[e], p2a[e + 1]} + (f32x2){w1[e], w1[e + 1]} * (f32x2){p1a[e], p1a[e + 1]} + (f32x2){w2[e], w2[e + 1]} * (f32x2){g8[e], g8[e + 1]} + (f32x2){bb[e], bb[e + 1]};
;                         const f32x2 r = gelu_tanh_mul2(gt, (f32x2){u8[e], u8[e + 1]}); o[e] = r.x; o[e + 1] = r.y; }
;                 }
;                 const int rloc = 128 * ai + 64 * wr + 16 * m + fr;
;                 if (!(B == 0 && m == 0 && fr < 2)) *(u32x4*)(ACT + (size_t)(u.pm * BM + rloc) * FF + chg) = pack8(o);
	v_cndmask_b32_e64 v114, v126, v128, s[40:41]
	v_cndmask_b32_e64 v126, v129, v127, s[38:39]
	v_mov_b32_e32 v127, v195
	v_mov_b32_e32 v128, v195
	v_mov_b32_e32 v129, v195
	v_mov_b32_e32 v130, v195
	v_pk_add_f32 v[118:119], v[118:119], 1.0 op_sel_hi:[1,0]
	v_mov_b32_dpp v127, v107 row_shr:1 row_mask:0xf bank_mask:0xf
	v_mov_b32_dpp v128, v107 row_shr:2 row_mask:0xf bank_mask:0xf
	v_mov_b32_dpp v129, v115 row_ror:1 row_mask:0xf bank_mask:0xf
	v_mov_b32_dpp v130, v115 row_ror:2 row_mask:0xf bank_mask:0xf
	v_rcp_f32_e32 v118, v118
	v_rcp_f32_e32 v119, v119
	v_pk_add_f32 v[120:121], v[120:121], 1.0 op_sel_hi:[1,0]
	v_cndmask_b32_e64 v115, v127, v129, s[40:41]
	v_cndmask_b32_e64 v127, v130, v128, s[38:39]
	v_mov_b32_e32 v128, v195
	v_mov_b32_e32 v129, v195
	v_mov_b32_e32 v130, v195
	v_mov_b32_e32 v131, v195
	v_rcp_f32_e32 v120, v120
	v_rcp_f32_e32 v121, v121
	v_mov_b32_dpp v128, v108 row_shr:1 row_mask:0xf bank_mask:0xf
	v_mov_b32_dpp v129, v108 row_shr:2 row_mask:0xf bank_mask:0xf
	v_mov_b32_dpp v130, v116 row_ror:1 row_mask:0xf bank_mask:0xf
	v_mov_b32_dpp v131, v116 row_ror:2 row_mask:0xf bank_mask:0xf
	v_cndmask_b32_e64 v116, v128, v130, s[40:41]
	v_cndmask_b32_e64 v128, v131, v129, s[38:39]
	v_mov_b32_e32 v129, v195
	v_mov_b32_e32 v130, v195
	v_mov_b32_e32 v131, v195
	v_mov_b32_e32 v132, v195
	v_mov_b32_dpp v129, v109 row_shr:1 row_mask:0xf bank_mask:0xf
	v_mov_b32_dpp v130, v109 row_shr:2 row_mask:0xf bank_mask:0xf
	v_mov_b32_dpp v131, v117 row_ror:1 row_mask:0xf bank_mask:0xf
	v_mov_b32_dpp v132, v117 row_ror:2 row_mask:0xf bank_mask:0xf
	v_pk_mul_f32 v[110:111], v[110:111], v[118:119]
	v_cndmask_b32_e64 v117, v129, v131, s[40:41]
	v_cndmask_b32_e64 v129, v132, v130, s[38:39]
	v_pk_mul_f32 v[86:87], v[86:87], v[110:111]
	v_pk_mul_f32 v[110:111], v[112:113], v[120:121]
	v_pk_mul_f32 v[112:113], v[66:67], v[126:127]
	v_pk_mul_f32 v[88:89], v[88:89], v[110:111]
	v_pk_fma_f32 v[112:113], v[70:71], v[114:115], v[112:113]
	v_pk_mul_f32 v[114:115], v[68:69], v[128:129]
	v_pk_fma_f32 v[106:107], v[106:107], v[74:75], v[112:113]
	v_pk_fma_f32 v[114:115], v[72:73], v[116:117], v[114:115]
	v_pk_add_f32 v[106:107], v[78:79], v[106:107]
	v_pk_fma_f32 v[108:109], v[108:109], v[76:77], v[114:115]
	v_pk_mul_f32 v[112:113], v[106:107], v[106:107]
	v_pk_add_f32 v[108:109], v[80:81], v[108:109]
	v_pk_fma_f32 v[112:113], v[112:113], s[78:79], 1.0 op_sel_hi:[1,0,0]
	v_pk_mul_f32 v[114:115], v[108:109], v[108:109]
	v_pk_mul_f32 v[112:113], v[106:107], v[112:113]
	v_pk_fma_f32 v[114:115], v[114:115], s[78:79], 1.0 op_sel_hi:[1,0,0]
	v_pk_mul_f32 v[112:113], v[112:113], s[24:25] op_sel_hi:[1,0]
	v_pk_mul_f32 v[114:115], v[108:109], v[114:115]
	v_exp_f32_e32 v112, v112
	v_exp_f32_e32 v113, v113
	v_pk_mul_f32 v[114:115], v[114:115], s[24:25] op_sel_hi:[1,0]
	v_mov_b32_e32 v110, 0
	v_exp_f32_e32 v114, v114
	v_exp_f32_e32 v115, v115
	v_pk_add_f32 v[112:113], v[112:113], 1.0 op_sel_hi:[1,0]
	v_mov_b32_e32 v111, 0
	v_rcp_f32_e32 v112, v112
	v_rcp_f32_e32 v113, v113
	v_pk_add_f32 v[114:115], v[114:115], 1.0 op_sel_hi:[1,0]
	v_pk_mul_f32 v[106:107], v[106:107], v[112:113]
	v_rcp_f32_e32 v114, v114
	v_rcp_f32_e32 v115, v115
	v_pk_mul_f32 v[106:107], v[82:83], v[106:107]
	v_mov_b32_e32 v112, 0
	v_mov_b32_e32 v113, 0
	v_pk_mul_f32 v[82:83], v[108:109], v[114:115]
	s_nop 0
	v_pk_mul_f32 v[108:109], v[84:85], v[82:83]
	v_cvt_pk_bf16_f32 v82, v86, v87
	v_or_b32_e32 v86, 48, v210
	v_mad_i64_i32 v[86:87], s[8:9], v86, s7, v[140:141]
	v_cvt_pk_bf16_f32 v83, v88, v89
	v_cvt_pk_bf16_f32 v84, v106, v107
	v_cvt_pk_bf16_f32 v85, v108, v109
	v_lshl_add_u64 v[86:87], v[86:87], 0, v[138:139]
	global_store_dwordx4 v[86:87], v[82:85], off sc1
	v_mov_b32_e32 v109, 0
	v_mov_b32_e32 v108, 0
	v_mov_b32_e32 v107, 0
	v_mov_b32_e32 v106, 0
	v_mov_b32_e32 v85, 0
	v_mov_b32_e32 v84, 0
	v_mov_b32_e32 v83, 0
	v_mov_b32_e32 v82, 0
	v_mov_b32_e32 v86, 0
	v_mov_b32_e32 v87, 0
	v_mov_b32_e32 v88, 0
	v_mov_b32_e32 v89, 0
	s_cbranch_vccnz .LBB0_86
	ds_read_b128 v[82:85], v207
	ds_read_b128 v[106:109], v207 offset:16
	ds_read_b128 v[86:89], v207 offset:512
	ds_read_b128 v[110:113], v207 offset:528
.LBB0_86:
	v_mov_b32_e32 v114, 0
	v_mov_b32_e32 v116, 0
	v_mov_b32_e32 v115, 0
	v_mov_b32_e32 v117, 0
	v_mov_b32_e32 v118, 0
	v_mov_b32_e32 v120, 0
	v_mov_b32_e32 v119, 0
	v_mov_b32_e32 v121, 0
	v_mov_b32_e32 v122, 0
	v_mov_b32_e32 v124, 0
	v_mov_b32_e32 v123, 0
	v_mov_b32_e32 v125, 0
	v_mov_b32_e32 v126, 0
	v_mov_b32_e32 v128, 0
	v_mov_b32_e32 v127, 0
	v_mov_b32_e32 v129, 0
	v_mov_b32_dpp v114, v54 row_shr:1 row_mask:0xf bank_mask:0xf
	v_mov_b32_dpp v116, v54 row_shr:2 row_mask:0xf bank_mask:0xf
	v_mov_b32_dpp v115, v55 row_shr:1 row_mask:0xf bank_mask:0xf
	v_mov_b32_dpp v117, v55 row_shr:2 row_mask:0xf bank_mask:0xf
	v_mov_b32_dpp v118, v56 row_shr:1 row_mask:0xf bank_mask:0xf
	v_mov_b32_dpp v120, v56 row_shr:2 row_mask:0xf bank_mask:0xf
	v_mov_b32_dpp v119, v57 row_shr:1 row_mask:0xf bank_mask:0xf
	v_mov_b32_dpp v121, v57 row_shr:2 row_mask:0xf bank_mask:0xf
	v_mov_b32_dpp v122, v50 row_shr:1 row_mask:0xf bank_mask:0xf
	v_mov_b32_dpp v124, v50 row_shr:2 row_mask:0xf bank_mask:0xf
	v_mov_b32_dpp v123, v51 row_shr:1 row_mask:0xf bank_mask:0xf
	v_mov_b32_dpp v125, v51 row_shr:2 row_mask:0xf bank_mask:0xf
	v_mov_b32_dpp v126, v52 row_shr:1 row_mask:0xf bank_mask:0xf
	v_mov_b32_dpp v128, v52 row_shr:2 row_mask:0xf bank_mask:0xf
	v_mov_b32_dpp v127, v53 row_shr:1 row_mask:0xf bank_mask:0xf
	v_mov_b32_dpp v129, v53 row_shr:2 row_mask:0xf bank_mask:0xf
	s_and_saveexec_b64 s[30:31], s[64:65]
	s_cbranch_execz .LBB0_88
; __device__ __forceinline__ u32x4 pack8(const float (&f)[8]) { u32x4 w; w.x = cvt_pk_bf16(f[0], f[1]); w.y = cvt_pk_bf16(f[2], f[3]); w.z = cvt_pk_bf16(f[4], f[5]); w.w = cvt_pk_bf16(f[6], f[7]); return w; }
; __device__ __forceinline__ float dpp_row_shr1(float x) { return __int_as_float(__builtin_amdgcn_update_dpp(0, __float_as_int(x), 0x111, 0xf, 0xf, false)); }
;     __device__ __forceinline__ void operator()(const f32x4 (&acc)[2][2][4][2], const Unit& u, int wr, int wc, int fr, int fq) const {
;     ...
;                     float p1a[8], p2a[8];
; #pragma unroll
;                     for (int e = 0; e < 8; ++e) { const float s1 = dpp_row_shr1(g8[e]), s2 = dpp_row_shr2(g8[e]);
;                         p1a[e] = (fr >= 1) ? s1 : q15[e]; p2a[e] = (fr >= 2) ? s2 : ((fr == 1) ? q15[e] : q14[e]); }
; #pragma unroll
;                     for (int e = 0; e < 8; e += 2) { const f32x2 gt = (f32x2){w0[e], w0[e + 1]} * (f32x2){p2a[e], p2a[e + 1]} + (f32x2){w1[e], w1[e + 1]} * (f32x2){p1a[e], p1a[e + 1]} + (f32x2){w2[e], w2[e + 1]} * (f32x2){g8[e], g8[e + 1]} + (f32x2){bb[e], bb[e + 1]};
;                         const f32x2 r = gelu_tanh_mul2(gt, (f32x2){u8[e], u8[e + 1]}); o[e] = r.x; o[e + 1] = r.y; }
;                 } else {
;                     float p1a[8], p2a[8];
; #pragma unroll
;                     for (int e = 0; e < 8; ++e) { const float pv = (e < 4) ? acc[ai][0][m - 1][0][e & 3] : acc[ai][0][m - 1][1][e & 3];
;                         const float s1 = dpp_row_shr1(g8[e]), s2 = dpp_row_shr2(g8[e]), r1 = dpp_row_ror1(pv), r2 = dpp_row_ror2(pv);
;                         p1a[e] = (fr >= 1) ? s1 : r1; p2a[e] = (fr >= 2) ? s2 : r2; }
; #pragma unroll
;                     for (int e = 0; e < 8; e += 2) { const f32x2 gt = (f32x2){w0[e], w0[e + 1]} * (f32x2){p2a[e], p2a[e + 1]} + (f32x2){w1[e], w1[e + 1]} * (f32x2){p1a[e], p1a[e + 1]} + (f32x2){w2[e], w2[e + 1]} * (f32x2){g8[e], g8[e + 1]} + (f32x2){bb[e], bb[e + 1]};
;                         const f32x2 r = gelu_tanh_mul2(gt, (f32x2){u8[e], u8[e + 1]}); o[e] = r.x; o[e + 1] = r.y; }
;                 }
;                 const int rloc = 128 * ai + 64 * wr + 16 * m + fr;
;                 if (!(B == 0 && m == 0 && fr < 2)) *(u32x4*)(ACT + (size_t)(u.pm * BM + rloc) * FF + chg) = pack8(o);
	s_waitcnt lgkmcnt(0)
	v_cndmask_b32_e64 v106, v106, v110, s[42:43]
	v_cndmask_b32_e64 v107, v107, v111, s[42:43]
	v_cndmask_b32_e64 v84, v84, v88, s[42:43]
	v_cndmask_b32_e64 v85, v85, v89, s[42:43]
	v_cndmask_b32_e64 v82, v82, v86, s[42:43]
	v_cndmask_b32_e64 v83, v83, v87, s[42:43]
	v_cndmask_b32_e64 v106, v106, v124, s[38:39]
	v_cndmask_b32_e64 v107, v107, v125, s[38:39]
	v_cndmask_b32_e64 v84, v84, v120, s[38:39]
	v_cndmask_b32_e64 v85, v85, v121, s[38:39]
	v_cndmask_b32_e64 v82, v82, v116, s[38:39]
	v_cndmask_b32_e64 v83, v83, v117, s[38:39]
	v_pk_mul_f32 v[106:107], v[66:67], v[106:107]
	v_cndmask_b32_e64 v110, v122, v110, s[40:41]
	v_cndmask_b32_e64 v111, v123, v111, s[40:41]
	v_pk_mul_f32 v[84:85], v[92:93], v[84:85]
	v_cndmask_b32_e64 v88, v118, v88, s[40:41]
	v_cndmask_b32_e64 v89, v119, v89, s[40:41]
	v_pk_mul_f32 v[82:83], v[90:91], v[82:83]
	v_cndmask_b32_e64 v86, v114, v86, s[40:41]
	v_cndmask_b32_e64 v87, v115, v87, s[40:41]
	v_pk_fma_f32 v[106:107], v[70:71], v[110:111], v[106:107]
	v_pk_fma_f32 v[84:85], v[96:97], v[88:89], v[84:85]
	v_pk_fma_f32 v[82:83], v[94:95], v[86:87], v[82:83]
	v_cndmask_b32_e64 v108, v108, v112, s[42:43]
	v_cndmask_b32_e64 v109, v109, v113, s[42:43]
	v_pk_fma_f32 v[106:107], v[50:51], v[74:75], v[106:107]
	v_pk_fma_f32 v[84:85], v[56:57], v[100:101], v[84:85]
	v_pk_fma_f32 v[82:83], v[54:55], v[98:99], v[82:83]
	v_cndmask_b32_e64 v108, v108, v128, s[38:39]
	v_cndmask_b32_e64 v109, v109, v129, s[38:39]
	v_pk_add_f32 v[106:107], v[78:79], v[106:107]
	v_pk_add_f32 v[84:85], v[104:105], v[84:85]
	v_pk_add_f32 v[82:83], v[102:103], v[82:83]
	v_pk_mul_f32 v[108:109], v[68:69], v[108:109]
	v_cndmask_b32_e64 v112, v126, v112, s[40:41]
	v_cndmask_b32_e64 v113, v127, v113, s[40:41]
	v_pk_mul_f32 v[110:111], v[106:107], v[106:107]
	v_pk_mul_f32 v[88:89], v[84:85], v[84:85]
	v_pk_mul_f32 v[86:87], v[82:83], v[82:83]
	v_pk_fma_f32 v[108:109], v[72:73], v[112:113], v[108:109]
	v_pk_fma_f32 v[110:111], v[110:111], s[78:79], 1.0 op_sel_hi:[1,0,0]
	v_pk_fma_f32 v[88:89], v[88:89], s[78:79], 1.0 op_sel_hi:[1,0,0]
	v_pk_fma_f32 v[86:87], v[86:87], s[78:79], 1.0 op_sel_hi:[1,0,0]
	v_pk_fma_f32 v[108:109], v[52:53], v[76:77], v[108:109]
	v_pk_mul_f32 v[110:111], v[106:107], v[110:111]
	v_pk_mul_f32 v[88:89], v[84:85], v[88:89]
	v_pk_mul_f32 v[86:87], v[82:83], v[86:87]
	v_pk_add_f32 v[108:109], v[80:81], v[108:109]
	v_pk_mul_f32 v[110:111], v[110:111], s[24:25] op_sel_hi:[1,0]
	v_pk_mul_f32 v[88:89], v[88:89], s[24:25] op_sel_hi:[1,0]
	v_pk_mul_f32 v[86:87], v[86:87], s[24:25] op_sel_hi:[1,0]
	v_pk_mul_f32 v[112:113], v[108:109], v[108:109]
	v_exp_f32_e32 v110, v110
	v_exp_f32_e32 v111, v111
	v_exp_f32_e32 v88, v88
	v_exp_f32_e32 v89, v89
	v_exp_f32_e32 v86, v86
	v_exp_f32_e32 v87, v87
	v_pk_fma_f32 v[112:113], v[112:113], s[78:79], 1.0 op_sel_hi:[1,0,0]
	v_pk_add_f32 v[110:111], v[110:111], 1.0 op_sel_hi:[1,0]
	v_pk_mul_f32 v[112:113], v[108:109], v[112:113]
	v_pk_add_f32 v[88:89], v[88:89], 1.0 op_sel_hi:[1,0]
	v_pk_mul_f32 v[112:113], v[112:113], s[24:25] op_sel_hi:[1,0]
	v_pk_add_f32 v[86:87], v[86:87], 1.0 op_sel_hi:[1,0]
	v_exp_f32_e32 v112, v112
	v_exp_f32_e32 v113, v113
	v_rcp_f32_e32 v110, v110
	v_rcp_f32_e32 v111, v111
	v_rcp_f32_e32 v88, v88
	v_rcp_f32_e32 v89, v89
	v_rcp_f32_e32 v86, v86
	v_rcp_f32_e32 v87, v87
	v_pk_add_f32 v[112:113], v[112:113], 1.0 op_sel_hi:[1,0]
	v_pk_mul_f32 v[106:107], v[106:107], v[110:111]
	v_rcp_f32_e32 v112, v112
	v_rcp_f32_e32 v113, v113
	v_pk_mul_f32 v[84:85], v[84:85], v[88:89]
	v_pk_mul_f32 v[82:83], v[82:83], v[86:87]
	v_readlane_b32 s8, v253, 57
	v_pk_mul_f32 v[62:63], v[62:63], v[106:107]
	v_pk_mul_f32 v[60:61], v[60:61], v[84:85]
	v_pk_mul_f32 v[58:59], v[58:59], v[82:83]
	v_readlane_b32 s9, v253, 58
	v_add_u32_e32 v122, 0x80, v210
	v_cvt_pk_bf16_f32 v58, v58, v59
	v_cvt_pk_bf16_f32 v59, v60, v61
	v_cvt_pk_bf16_f32 v60, v62, v63
	v_pk_mul_f32 v[108:109], v[108:109], v[112:113]
	v_mov_b64_e32 v[62:63], s[8:9]
	v_mad_i64_i32 v[62:63], s[8:9], v122, s10, v[62:63]
	v_lshl_add_u64 v[62:63], v[192:193], 1, v[62:63]
	v_pk_mul_f32 v[64:65], v[64:65], v[108:109]
	s_nop 0
	v_cvt_pk_bf16_f32 v61, v64, v65
	global_store_dwordx4 v[62:63], v[58:61], off sc1
.LBB0_88:
	s_or_b64 exec, exec, s[30:31]
	s_nop 0
	v_mov_b32_e32 v58, v195
	v_mov_b32_e32 v59, v195
	v_mov_b32_e32 v60, v195
	v_mov_b32_e32 v61, v195
	v_mov_b32_dpp v58, v38 row_shr:1 row_mask:0xf bank_mask:0xf
	v_mov_b32_dpp v59, v38 row_shr:2 row_mask:0xf bank_mask:0xf
	v_mov_b32_dpp v60, v54 row_ror:1 row_mask:0xf bank_mask:0xf
	v_mov_b32_dpp v61, v54 row_ror:2 row_mask:0xf bank_mask:0xf
	v_cndmask_b32_e64 v54, v58, v60, s[40:41]
	v_cndmask_b32_e64 v58, v61, v59, s[38:39]
	v_mov_b32_e32 v59, v195
	v_mov_b32_e32 v60, v195
	v_mov_b32_e32 v61, v195
	v_mov_b32_e32 v62, v195
	v_mov_b32_dpp v59, v39 row_shr:1 row_mask:0xf bank_mask:0xf
	v_mov_b32_dpp v60, v39 row_shr:2 row_mask:0xf bank_mask:0xf
	v_mov_b32_dpp v61, v55 row_ror:1 row_mask:0xf bank_mask:0xf
	v_mov_b32_dpp v62, v55 row_ror:2 row_mask:0xf bank_mask:0xf
	v_cndmask_b32_e64 v55, v59, v61, s[40:41]
	v_cndmask_b32_e64 v59, v62, v60, s[38:39]
	v_mov_b32_e32 v60, v195
	v_mov_b32_e32 v61, v195
	v_mov_b32_e32 v62, v195
	v_mov_b32_e32 v63, v195
	v_mov_b32_dpp v60, v40 row_shr:1 row_mask:0xf bank_mask:0xf
	v_mov_b32_dpp v61, v40 row_shr:2 row_mask:0xf bank_mask:0xf
	v_mov_b32_dpp v62, v56 row_ror:1 row_mask:0xf bank_mask:0xf
	v_mov_b32_dpp v63, v56 row_ror:2 row_mask:0xf bank_mask:0xf
	v_cndmask_b32_e64 v56, v60, v62, s[40:41]
	v_cndmask_b32_e64 v60, v63, v61, s[38:39]
	v_mov_b32_e32 v61, v195
	v_mov_b32_e32 v62, v195
	v_mov_b32_e32 v63, v195
	v_mov_b32_e32 v64, v195
; __device__ __forceinline__ u32x4 pack8(const float (&f)[8]) { u32x4 w; w.x = cvt_pk_bf16(f[0], f[1]); w.y = cvt_pk_bf16(f[2], f[3]); w.z = cvt_pk_bf16(f[4], f[5]); w.w = cvt_pk_bf16(f[6], f[7]); return w; }
; __device__ __forceinline__ float dpp_row_shr1(float x) { return __int_as_float(__builtin_amdgcn_update_dpp(0, __float_as_int(x), 0x111, 0xf, 0xf, false)); }
; __device__ __forceinline__ float dpp_row_shr2(float x) { return __int_as_float(__builtin_amdgcn_update_dpp(0, __float_as_int(x), 0x112, 0xf, 0xf, false)); }
; __device__ __forceinline__ float dpp_row_ror1(float x) { return __int_as_float(__builtin_amdgcn_update_dpp(0, __float_as_int(x), 0x121, 0xf, 0xf, false)); }
; __device__ __forceinline__ float dpp_row_ror2(float x) { return __int_as_float(__builtin_amdgcn_update_dpp(0, __float_as_int(x), 0x122, 0xf, 0xf, false)); }
;     __device__ __forceinline__ void operator()(const f32x4 (&acc)[2][2][4][2], const Unit& u, int wr, int wc, int fr, int fq) const {
;     ...
;                     float p1a[8], p2a[8];
; #pragma unroll
;                     for (int e = 0; e < 8; ++e) { const float pv = (e < 4) ? acc[ai][0][m - 1][0][e & 3] : acc[ai][0][m - 1][1][e & 3];
;                         const float s1 = dpp_row_shr1(g8[e]), s2 = dpp_row_shr2(g8[e]), r1 = dpp_row_ror1(pv), r2 = dpp_row_ror2(pv);
;                         p1a[e] = (fr >= 1) ? s1 : r1; p2a[e] = (fr >= 2) ? s2 : r2; }
; #pragma unroll
;                     for (int e = 0; e < 8; e += 2) { const f32x2 gt = (f32x2){w0[e], w0[e + 1]} * (f32x2){p2a[e], p2a[e + 1]} + (f32x2){w1[e], w1[e + 1]} * (f32x2){p1a[e], p1a[e + 1]} + (f32x2){w2[e], w2[e + 1]} * (f32x2){g8[e], g8[e + 1]} + (f32x2){bb[e], bb[e + 1]};
;                         const f32x2 r = gelu_tanh_mul2(gt, (f32x2){u8[e], u8[e + 1]}); o[e] = r.x; o[e + 1] = r.y; }
;                 }
;                 const int rloc = 128 * ai + 64 * wr + 16 * m + fr;
;                 if (!(B == 0 && m == 0 && fr < 2)) *(u32x4*)(ACT + (size_t)(u.pm * BM + rloc) * FF + chg) = pack8(o);
	v_mov_b32_dpp v61, v41 row_shr:1 row_mask:0xf bank_mask:0xf
	v_mov_b32_dpp v62, v41 row_shr:2 row_mask:0xf bank_mask:0xf
	v_mov_b32_dpp v63, v57 row_ror:1 row_mask:0xf bank_mask:0xf
	v_mov_b32_dpp v64, v57 row_ror:2 row_mask:0xf bank_mask:0xf
	v_cndmask_b32_e64 v57, v61, v63, s[40:41]
	v_cndmask_b32_e64 v61, v64, v62, s[38:39]
	v_pk_mul_f32 v[58:59], v[90:91], v[58:59]
	v_pk_mul_f32 v[60:61], v[92:93], v[60:61]
	v_pk_fma_f32 v[54:55], v[94:95], v[54:55], v[58:59]
	v_pk_fma_f32 v[56:57], v[96:97], v[56:57], v[60:61]
	v_pk_fma_f32 v[54:55], v[38:39], v[98:99], v[54:55]
	v_pk_fma_f32 v[56:57], v[40:41], v[100:101], v[56:57]
	v_pk_add_f32 v[54:55], v[102:103], v[54:55]
	v_pk_add_f32 v[56:57], v[104:105], v[56:57]
	v_pk_mul_f32 v[58:59], v[54:55], v[54:55]
	v_pk_mul_f32 v[60:61], v[56:57], v[56:57]
	v_pk_fma_f32 v[58:59], v[58:59], s[78:79], 1.0 op_sel_hi:[1,0,0]
	v_pk_fma_f32 v[60:61], v[60:61], s[78:79], 1.0 op_sel_hi:[1,0,0]
	v_pk_mul_f32 v[58:59], v[54:55], v[58:59]
	v_pk_mul_f32 v[60:61], v[56:57], v[60:61]
	v_pk_mul_f32 v[58:59], v[58:59], s[24:25] op_sel_hi:[1,0]
	v_pk_mul_f32 v[60:61], v[60:61], s[24:25] op_sel_hi:[1,0]
	v_exp_f32_e32 v58, v58
	v_exp_f32_e32 v59, v59
	v_exp_f32_e32 v60, v60
	v_exp_f32_e32 v61, v61
	v_mov_b32_e32 v62, v195
	v_mov_b32_e32 v63, v195
	v_mov_b32_e32 v64, v195
	v_mov_b32_e32 v65, v195
	v_mov_b32_dpp v62, v34 row_shr:1 row_mask:0xf bank_mask:0xf
	v_mov_b32_dpp v63, v34 row_shr:2 row_mask:0xf bank_mask:0xf
	v_mov_b32_dpp v64, v50 row_ror:1 row_mask:0xf bank_mask:0xf
	v_mov_b32_dpp v65, v50 row_ror:2 row_mask:0xf bank_mask:0xf
	v_cndmask_b32_e64 v50, v62, v64, s[40:41]
	v_cndmask_b32_e64 v62, v65, v63, s[38:39]
	v_mov_b32_e32 v63, v195
	v_mov_b32_e32 v64, v195
	v_mov_b32_e32 v65, v195
	s_waitcnt lgkmcnt(3)
	v_mov_b32_e32 v82, v195
	v_pk_add_f32 v[58:59], v[58:59], 1.0 op_sel_hi:[1,0]
	v_mov_b32_dpp v63, v35 row_shr:1 row_mask:0xf bank_mask:0xf
	v_mov_b32_dpp v64, v35 row_shr:2 row_mask:0xf bank_mask:0xf
	v_mov_b32_dpp v65, v51 row_ror:1 row_mask:0xf bank_mask:0xf
	v_mov_b32_dpp v82, v51 row_ror:2 row_mask:0xf bank_mask:0xf
	v_rcp_f32_e32 v58, v58
	v_rcp_f32_e32 v59, v59
	v_pk_add_f32 v[60:61], v[60:61], 1.0 op_sel_hi:[1,0]
	v_cndmask_b32_e64 v51, v63, v65, s[40:41]
	v_cndmask_b32_e64 v63, v82, v64, s[38:39]
	v_mov_b32_e32 v64, v195
	v_mov_b32_e32 v65, v195
	v_mov_b32_e32 v82, v195
	v_mov_b32_e32 v83, v195
	v_rcp_f32_e32 v60, v60
	v_rcp_f32_e32 v61, v61
	v_mov_b32_dpp v64, v36 row_shr:1 row_mask:0xf bank_mask:0xf
	v_mov_b32_dpp v65, v36 row_shr:2 row_mask:0xf bank_mask:0xf
	v_mov_b32_dpp v82, v52 row_ror:1 row_mask:0xf bank_mask:0xf
	v_mov_b32_dpp v83, v52 row_ror:2 row_mask:0xf bank_mask:0xf
	v_cndmask_b32_e64 v52, v64, v82, s[40:41]
	v_cndmask_b32_e64 v64, v83, v65, s[38:39]
	v_mov_b32_e32 v65, v195
	v_mov_b32_e32 v82, v195
	v_mov_b32_e32 v83, v195
	v_mov_b32_e32 v84, v195
	v_mov_b32_dpp v65, v37 row_shr:1 row_mask:0xf bank_mask:0xf
	v_mov_b32_dpp v82, v37 row_shr:2 row_mask:0xf bank_mask:0xf
	v_mov_b32_dpp v83, v53 row_ror:1 row_mask:0xf bank_mask:0xf
	v_mov_b32_dpp v84, v53 row_ror:2 row_mask:0xf bank_mask:0xf
	v_pk_mul_f32 v[54:55], v[54:55], v[58:59]
	v_cndmask_b32_e64 v53, v65, v83, s[40:41]
	v_cndmask_b32_e64 v65, v84, v82, s[38:39]
	v_pk_mul_f32 v[46:47], v[46:47], v[54:55]
	v_pk_mul_f32 v[54:55], v[56:57], v[60:61]
	v_pk_mul_f32 v[56:57], v[66:67], v[62:63]
	v_pk_mul_f32 v[58:59], v[68:69], v[64:65]
	v_pk_fma_f32 v[50:51], v[70:71], v[50:51], v[56:57]
	v_pk_fma_f32 v[52:53], v[72:73], v[52:53], v[58:59]
	v_pk_fma_f32 v[50:51], v[34:35], v[74:75], v[50:51]
	v_pk_fma_f32 v[52:53], v[36:37], v[76:77], v[52:53]
	v_pk_add_f32 v[50:51], v[78:79], v[50:51]
	v_pk_add_f32 v[52:53], v[80:81], v[52:53]
	v_pk_mul_f32 v[56:57], v[50:51], v[50:51]
	v_pk_mul_f32 v[58:59], v[52:53], v[52:53]
	v_pk_fma_f32 v[56:57], v[56:57], s[78:79], 1.0 op_sel_hi:[1,0,0]
	v_pk_fma_f32 v[58:59], v[58:59], s[78:79], 1.0 op_sel_hi:[1,0,0]
	v_pk_mul_f32 v[56:57], v[50:51], v[56:57]
	v_pk_mul_f32 v[58:59], v[52:53], v[58:59]
	v_pk_mul_f32 v[56:57], v[56:57], s[24:25] op_sel_hi:[1,0]
	v_pk_mul_f32 v[58:59], v[58:59], s[24:25] op_sel_hi:[1,0]
	v_exp_f32_e32 v56, v56
	v_exp_f32_e32 v57, v57
	v_exp_f32_e32 v58, v58
	v_exp_f32_e32 v59, v59
	v_readlane_b32 s8, v253, 57
	v_pk_add_f32 v[56:57], v[56:57], 1.0 op_sel_hi:[1,0]
	v_pk_mul_f32 v[48:49], v[48:49], v[54:55]
	v_rcp_f32_e32 v56, v56
	v_rcp_f32_e32 v57, v57
	v_pk_add_f32 v[58:59], v[58:59], 1.0 op_sel_hi:[1,0]
	v_readlane_b32 s9, v253, 58
	v_rcp_f32_e32 v58, v58
	v_rcp_f32_e32 v59, v59
	v_pk_mul_f32 v[50:51], v[50:51], v[56:57]
	v_mov_b32_e32 v54, v195
	v_pk_mul_f32 v[42:43], v[42:43], v[50:51]
	v_pk_mul_f32 v[50:51], v[52:53], v[58:59]
	v_mov_b32_e32 v52, v195
	v_pk_mul_f32 v[50:51], v[44:45], v[50:51]
	v_cvt_pk_bf16_f32 v44, v46, v47
	v_cvt_pk_bf16_f32 v45, v48, v49
	v_cvt_pk_bf16_f32 v46, v42, v43
	v_add_u32_e32 v48, 0x90, v210
	v_mov_b64_e32 v[42:43], s[8:9]
	v_mad_i64_i32 v[48:49], s[8:9], v48, s7, v[42:43]
	v_cvt_pk_bf16_f32 v47, v50, v51
	v_lshl_add_u64 v[48:49], v[48:49], 0, v[138:139]
	global_store_dwordx4 v[48:49], v[44:47], off sc1
	v_mov_b32_e32 v48, v195
	v_mov_b32_e32 v49, v195
	v_mov_b32_e32 v44, v195
	v_mov_b32_e32 v45, v195
	v_mov_b32_e32 v46, v195
	v_mov_b32_e32 v47, v195
	v_mov_b32_dpp v44, v22 row_shr:1 row_mask:0xf bank_mask:0xf
	v_mov_b32_dpp v45, v22 row_shr:2 row_mask:0xf bank_mask:0xf
	v_mov_b32_dpp v46, v38 row_ror:1 row_mask:0xf bank_mask:0xf
	v_mov_b32_dpp v47, v38 row_ror:2 row_mask:0xf bank_mask:0xf
	v_cndmask_b32_e64 v38, v44, v46, s[40:41]
	v_cndmask_b32_e64 v44, v47, v45, s[38:39]
	v_mov_b32_e32 v45, v195
	v_mov_b32_e32 v46, v195
	v_mov_b32_e32 v47, v195
; __device__ __forceinline__ u32x4 pack8(const float (&f)[8]) { u32x4 w; w.x = cvt_pk_bf16(f[0], f[1]); w.y = cvt_pk_bf16(f[2], f[3]); w.z = cvt_pk_bf16(f[4], f[5]); w.w = cvt_pk_bf16(f[6], f[7]); return w; }
; __device__ __forceinline__ float dpp_row_shr1(float x) { return __int_as_float(__builtin_amdgcn_update_dpp(0, __float_as_int(x), 0x111, 0xf, 0xf, false)); }
; __device__ __forceinline__ float dpp_row_shr2(float x) { return __int_as_float(__builtin_amdgcn_update_dpp(0, __float_as_int(x), 0x112, 0xf, 0xf, false)); }
; __device__ __forceinline__ float dpp_row_ror1(float x) { return __int_as_float(__builtin_amdgcn_update_dpp(0, __float_as_int(x), 0x121, 0xf, 0xf, false)); }
; __device__ __forceinline__ float dpp_row_ror2(float x) { return __int_as_float(__builtin_amdgcn_update_dpp(0, __float_as_int(x), 0x122, 0xf, 0xf, false)); }
;     __device__ __forceinline__ void operator()(const f32x4 (&acc)[2][2][4][2], const Unit& u, int wr, int wc, int fr, int fq) const {
;     ...
;                     float p1a[8], p2a[8];
; #pragma unroll
;                     for (int e = 0; e < 8; ++e) { const float pv = (e < 4) ? acc[ai][0][m - 1][0][e & 3] : acc[ai][0][m - 1][1][e & 3];
;                         const float s1 = dpp_row_shr1(g8[e]), s2 = dpp_row_shr2(g8[e]), r1 = dpp_row_ror1(pv), r2 = dpp_row_ror2(pv);
;                         p1a[e] = (fr >= 1) ? s1 : r1; p2a[e] = (fr >= 2) ? s2 : r2; }
; #pragma unroll
;                     for (int e = 0; e < 8; e += 2) { const f32x2 gt = (f32x2){w0[e], w0[e + 1]} * (f32x2){p2a[e], p2a[e + 1]} + (f32x2){w1[e], w1[e + 1]} * (f32x2){p1a[e], p1a[e + 1]} + (f32x2){w2[e], w2[e + 1]} * (f32x2){g8[e], g8[e + 1]} + (f32x2){bb[e], bb[e + 1]};
;                         const f32x2 r = gelu_tanh_mul2(gt, (f32x2){u8[e], u8[e + 1]}); o[e] = r.x; o[e + 1] = r.y; }
;                 }
;                 const int rloc = 128 * ai + 64 * wr + 16 * m + fr;
;                 if (!(B == 0 && m == 0 && fr < 2)) *(u32x4*)(ACT + (size_t)(u.pm * BM + rloc) * FF + chg) = pack8(o);
	v_mov_b32_dpp v45, v23 row_shr:1 row_mask:0xf bank_mask:0xf
	v_mov_b32_dpp v46, v23 row_shr:2 row_mask:0xf bank_mask:0xf
	v_mov_b32_dpp v47, v39 row_ror:1 row_mask:0xf bank_mask:0xf
	v_mov_b32_dpp v48, v39 row_ror:2 row_mask:0xf bank_mask:0xf
	v_cndmask_b32_e64 v39, v45, v47, s[40:41]
	v_cndmask_b32_e64 v45, v48, v46, s[38:39]
	v_mov_b32_e32 v46, v195
	v_mov_b32_e32 v47, v195
	v_mov_b32_e32 v48, v195
	v_mov_b32_dpp v46, v24 row_shr:1 row_mask:0xf bank_mask:0xf
	v_mov_b32_dpp v47, v24 row_shr:2 row_mask:0xf bank_mask:0xf
	v_mov_b32_dpp v48, v40 row_ror:1 row_mask:0xf bank_mask:0xf
	v_mov_b32_dpp v49, v40 row_ror:2 row_mask:0xf bank_mask:0xf
	v_cndmask_b32_e64 v40, v46, v48, s[40:41]
	v_cndmask_b32_e64 v46, v49, v47, s[38:39]
	v_mov_b32_e32 v47, v195
	v_mov_b32_e32 v48, v195
	v_mov_b32_e32 v49, v195
	v_mov_b32_e32 v50, v195
	v_mov_b32_dpp v47, v25 row_shr:1 row_mask:0xf bank_mask:0xf
	v_mov_b32_dpp v48, v25 row_shr:2 row_mask:0xf bank_mask:0xf
	v_mov_b32_dpp v49, v41 row_ror:1 row_mask:0xf bank_mask:0xf
	v_mov_b32_dpp v50, v41 row_ror:2 row_mask:0xf bank_mask:0xf
	v_cndmask_b32_e64 v41, v47, v49, s[40:41]
	v_cndmask_b32_e64 v47, v50, v48, s[38:39]
	v_pk_mul_f32 v[44:45], v[90:91], v[44:45]
	v_pk_mul_f32 v[46:47], v[92:93], v[46:47]
	v_pk_fma_f32 v[38:39], v[94:95], v[38:39], v[44:45]
	v_pk_fma_f32 v[40:41], v[96:97], v[40:41], v[46:47]
	v_pk_fma_f32 v[38:39], v[22:23], v[98:99], v[38:39]
	v_pk_fma_f32 v[40:41], v[24:25], v[100:101], v[40:41]
	v_pk_add_f32 v[38:39], v[102:103], v[38:39]
	v_pk_add_f32 v[40:41], v[104:105], v[40:41]
	v_pk_mul_f32 v[44:45], v[38:39], v[38:39]
	v_pk_mul_f32 v[46:47], v[40:41], v[40:41]
	v_pk_fma_f32 v[44:45], v[44:45], s[78:79], 1.0 op_sel_hi:[1,0,0]
	v_pk_fma_f32 v[46:47], v[46:47], s[78:79], 1.0 op_sel_hi:[1,0,0]
	v_pk_mul_f32 v[44:45], v[38:39], v[44:45]
	v_pk_mul_f32 v[46:47], v[40:41], v[46:47]
	v_pk_mul_f32 v[44:45], v[44:45], s[24:25] op_sel_hi:[1,0]
	v_pk_mul_f32 v[46:47], v[46:47], s[24:25] op_sel_hi:[1,0]
	v_exp_f32_e32 v44, v44
	v_exp_f32_e32 v45, v45
	v_exp_f32_e32 v46, v46
	v_exp_f32_e32 v47, v47
	v_mov_b32_e32 v48, v195
	v_mov_b32_e32 v49, v195
	v_mov_b32_e32 v50, v195
	v_mov_b32_e32 v51, v195
	v_mov_b32_dpp v48, v18 row_shr:1 row_mask:0xf bank_mask:0xf
	v_mov_b32_dpp v49, v18 row_shr:2 row_mask:0xf bank_mask:0xf
	v_mov_b32_dpp v50, v34 row_ror:1 row_mask:0xf bank_mask:0xf
	v_mov_b32_dpp v51, v34 row_ror:2 row_mask:0xf bank_mask:0xf
	v_cndmask_b32_e64 v34, v48, v50, s[40:41]
	v_cndmask_b32_e64 v48, v51, v49, s[38:39]
	v_mov_b32_e32 v49, v195
	v_mov_b32_e32 v50, v195
	v_mov_b32_e32 v51, v195
	v_pk_add_f32 v[44:45], v[44:45], 1.0 op_sel_hi:[1,0]
	v_mov_b32_dpp v49, v19 row_shr:1 row_mask:0xf bank_mask:0xf
	v_mov_b32_dpp v50, v19 row_shr:2 row_mask:0xf bank_mask:0xf
	v_mov_b32_dpp v51, v35 row_ror:1 row_mask:0xf bank_mask:0xf
	v_mov_b32_dpp v52, v35 row_ror:2 row_mask:0xf bank_mask:0xf
	v_rcp_f32_e32 v44, v44
	v_rcp_f32_e32 v45, v45
	v_pk_add_f32 v[46:47], v[46:47], 1.0 op_sel_hi:[1,0]
	v_cndmask_b32_e64 v35, v49, v51, s[40:41]
	v_cndmask_b32_e64 v49, v52, v50, s[38:39]
	v_mov_b32_e32 v50, v195
	v_mov_b32_e32 v51, v195
	v_mov_b32_e32 v52, v195
	v_mov_b32_e32 v53, v195
	v_rcp_f32_e32 v46, v46
	v_rcp_f32_e32 v47, v47
	v_mov_b32_dpp v50, v20 row_shr:1 row_mask:0xf bank_mask:0xf
	v_mov_b32_dpp v51, v20 row_shr:2 row_mask:0xf bank_mask:0xf
	v_mov_b32_dpp v52, v36 row_ror:1 row_mask:0xf bank_mask:0xf
	v_mov_b32_dpp v53, v36 row_ror:2 row_mask:0xf bank_mask:0xf
	v_cndmask_b32_e64 v36, v50, v52, s[40:41]
	v_cndmask_b32_e64 v50, v53, v51, s[38:39]
	v_mov_b32_e32 v51, v195
	v_mov_b32_e32 v52, v195
	v_mov_b32_e32 v53, v195
	v_mov_b32_dpp v51, v21 row_shr:1 row_mask:0xf bank_mask:0xf
	v_mov_b32_dpp v52, v21 row_shr:2 row_mask:0xf bank_mask:0xf
	v_mov_b32_dpp v53, v37 row_ror:1 row_mask:0xf bank_mask:0xf
	v_mov_b32_dpp v54, v37 row_ror:2 row_mask:0xf bank_mask:0xf
	v_pk_mul_f32 v[38:39], v[38:39], v[44:45]
	v_cndmask_b32_e64 v37, v51, v53, s[40:41]
	v_cndmask_b32_e64 v51, v54, v52, s[38:39]
	v_pk_mul_f32 v[30:31], v[30:31], v[38:39]
	v_pk_mul_f32 v[38:39], v[40:41], v[46:47]
	v_pk_mul_f32 v[40:41], v[66:67], v[48:49]
	v_pk_mul_f32 v[44:45], v[68:69], v[50:51]
	v_pk_fma_f32 v[34:35], v[70:71], v[34:35], v[40:41]
	v_pk_fma_f32 v[36:37], v[72:73], v[36:37], v[44:45]
	v_pk_fma_f32 v[34:35], v[18:19], v[74:75], v[34:35]
	v_pk_fma_f32 v[36:37], v[20:21], v[76:77], v[36:37]
	v_pk_add_f32 v[34:35], v[78:79], v[34:35]
	v_pk_add_f32 v[36:37], v[80:81], v[36:37]
	v_pk_mul_f32 v[40:41], v[34:35], v[34:35]
	v_pk_mul_f32 v[44:45], v[36:37], v[36:37]
	v_pk_fma_f32 v[40:41], v[40:41], s[78:79], 1.0 op_sel_hi:[1,0,0]
	v_pk_fma_f32 v[44:45], v[44:45], s[78:79], 1.0 op_sel_hi:[1,0,0]
	v_pk_mul_f32 v[40:41], v[34:35], v[40:41]
	v_pk_mul_f32 v[44:45], v[36:37], v[44:45]
	v_pk_mul_f32 v[40:41], v[40:41], s[24:25] op_sel_hi:[1,0]
	v_pk_mul_f32 v[44:45], v[44:45], s[24:25] op_sel_hi:[1,0]
	v_exp_f32_e32 v40, v40
	v_exp_f32_e32 v41, v41
	v_exp_f32_e32 v44, v44
	v_exp_f32_e32 v45, v45
	v_pk_mul_f32 v[32:33], v[32:33], v[38:39]
	v_pk_add_f32 v[40:41], v[40:41], 1.0 op_sel_hi:[1,0]
	s_andn2_b64 vcc, exec, s[44:45]
	v_rcp_f32_e32 v40, v40
	v_rcp_f32_e32 v41, v41
	v_pk_add_f32 v[44:45], v[44:45], 1.0 op_sel_hi:[1,0]
	s_mov_b64 s[30:31], -1
	v_rcp_f32_e32 v44, v44
	v_rcp_f32_e32 v45, v45
	v_pk_mul_f32 v[34:35], v[34:35], v[40:41]
	s_nop 0
	v_pk_mul_f32 v[34:35], v[26:27], v[34:35]
	v_pk_mul_f32 v[26:27], v[36:37], v[44:45]
	s_nop 0
	v_pk_mul_f32 v[36:37], v[28:29], v[26:27]
	v_cvt_pk_bf16_f32 v26, v30, v31
	v_add_u32_e32 v30, 0xa0, v210
	v_mad_i64_i32 v[30:31], s[8:9], v30, s7, v[42:43]
	v_cvt_pk_bf16_f32 v27, v32, v33
	v_cvt_pk_bf16_f32 v28, v34, v35
; #define PG8_BAR __builtin_amdgcn_s_barrier()
; template <class Epi>
; __device__ __forceinline__ void gemm_phase(LAS unsigned char* lds, const Gemm g, const Order& S, const Epi& E) {
;     ...
;     for (;;) {
;         const bool has_next = S.next(ui + 1, nxt);
;         const char* nA = has_next ? (const char*)(g.A + (size_t)nxt.g * g.gA) + (size_t)nxt.pm * tstepA : cA; const char* nB = has_next ? (const char*)(g.Bt + (size_t)nxt.g * g.gB) + (size_t)nxt.pn * tstepB : cB;
;         for (int t = 0; t < nt; t += 2) {
;             const bool last = (t == nt - 2);
;             const char* a1 = cA + (size_t)(t + 1) * kstep;
;             const char* a2 = last ? nA : cA + (size_t)(t + 2) * kstep; const char* b2 = last ? nB : cB + (size_t)(t + 2) * kstep;
;             const char* a3 = a2 + kstep; const char* b3 = b2 + kstep;
;             PG8_LDB(B0, 0, 0); PG8_LDB(B1, 0, 1); PG8_SCHED; PG8_LDA(At, 0, 0); PG8_STAGE(PG8_SA(1, 1), a1 + hstepA, voffA);
;             PG8_WAIT_V(8); PG8_WAIT_L(0); PG8_BAR; PG8_MMA(0, 0, At, B0); PG8_MMA(0, 1, At, B1); PG8_BAR; PG8_SCHED;
;             PG8_LDA(At, 0, 1); PG8_STAGE(PG8_SB(0, 0), b2, voffB); PG8_STAGE(PG8_SB(0, 1), b2 + hstepB, voffB); PG8_STAGE(PG8_SA(0, 0), a2, voffA);
;     __device__ __forceinline__ void operator()(const f32x4 (&acc)[2][2][4][2], const Unit& u, int wr, int wc, int fr, int fq) const {
;     ...
;                     float p1a[8], p2a[8];
; #pragma unroll
;                     for (int e = 0; e < 8; ++e) { const float pv = (e < 4) ? acc[ai][0][m - 1][0][e & 3] : acc[ai][0][m - 1][1][e & 3];
;                         const float s1 = dpp_row_shr1(g8[e]), s2 = dpp_row_shr2(g8[e]), r1 = dpp_row_ror1(pv), r2 = dpp_row_ror2(pv);
;                         p1a[e] = (fr >= 1) ? s1 : r1; p2a[e] = (fr >= 2) ? s2 : r2; }
; #pragma unroll
;                     for (int e = 0; e < 8; e += 2) { const f32x2 gt = (f32x2){w0[e], w0[e + 1]} * (f32x2){p2a[e], p2a[e + 1]} + (f32x2){w1[e], w1[e + 1]} * (f32x2){p1a[e], p1a[e + 1]} + (f32x2){w2[e], w2[e + 1]} * (f32x2){g8[e], g8[e + 1]} + (f32x2){bb[e], bb[e + 1]};
;                         const f32x2 r = gelu_tanh_mul2(gt, (f32x2){u8[e], u8[e + 1]}); o[e] = r.x; o[e + 1] = r.y; }
;                 }
;                 const int rloc = 128 * ai + 64 * wr + 16 * m + fr;
;                 if (!(B == 0 && m == 0 && fr < 2)) *(u32x4*)(ACT + (size_t)(u.pm * BM + rloc) * FF + chg) = pack8(o);
	v_cvt_pk_bf16_f32 v29, v36, v37
	v_lshl_add_u64 v[30:31], v[30:31], 0, v[138:139]
	global_store_dwordx4 v[30:31], v[26:29], off sc1
	v_mov_b32_e32 v30, v195
	v_mov_b32_e32 v31, v195
	v_mov_b32_e32 v26, v195
	v_mov_b32_e32 v27, v195
	v_mov_b32_e32 v28, v195
	v_mov_b32_e32 v29, v195
	v_mov_b32_dpp v26, v14 row_shr:1 row_mask:0xf bank_mask:0xf
	v_mov_b32_dpp v27, v14 row_shr:2 row_mask:0xf bank_mask:0xf
	v_mov_b32_dpp v28, v22 row_ror:1 row_mask:0xf bank_mask:0xf
	v_mov_b32_dpp v29, v22 row_ror:2 row_mask:0xf bank_mask:0xf
	v_cndmask_b32_e64 v22, v26, v28, s[40:41]
	v_cndmask_b32_e64 v26, v29, v27, s[38:39]
	v_mov_b32_e32 v27, v195
	v_mov_b32_e32 v28, v195
	v_mov_b32_e32 v29, v195
	v_mov_b32_dpp v27, v15 row_shr:1 row_mask:0xf bank_mask:0xf
	v_mov_b32_dpp v28, v15 row_shr:2 row_mask:0xf bank_mask:0xf
	v_mov_b32_dpp v29, v23 row_ror:1 row_mask:0xf bank_mask:0xf
	v_mov_b32_dpp v30, v23 row_ror:2 row_mask:0xf bank_mask:0xf
	v_cndmask_b32_e64 v23, v27, v29, s[40:41]
	v_cndmask_b32_e64 v27, v30, v28, s[38:39]
	v_mov_b32_e32 v28, v195
	v_mov_b32_e32 v29, v195
	v_mov_b32_e32 v30, v195
	v_mov_b32_dpp v28, v16 row_shr:1 row_mask:0xf bank_mask:0xf
	v_mov_b32_dpp v29, v16 row_shr:2 row_mask:0xf bank_mask:0xf
	v_mov_b32_dpp v30, v24 row_ror:1 row_mask:0xf bank_mask:0xf
	v_mov_b32_dpp v31, v24 row_ror:2 row_mask:0xf bank_mask:0xf
	v_cndmask_b32_e64 v24, v28, v30, s[40:41]
	v_cndmask_b32_e64 v28, v31, v29, s[38:39]
	v_mov_b32_e32 v29, v195
	v_mov_b32_e32 v30, v195
	v_mov_b32_e32 v31, v195
	v_mov_b32_e32 v32, v195
	v_mov_b32_dpp v29, v17 row_shr:1 row_mask:0xf bank_mask:0xf
	v_mov_b32_dpp v30, v17 row_shr:2 row_mask:0xf bank_mask:0xf
	v_mov_b32_dpp v31, v25 row_ror:1 row_mask:0xf bank_mask:0xf
	v_mov_b32_dpp v32, v25 row_ror:2 row_mask:0xf bank_mask:0xf
	v_cndmask_b32_e64 v25, v29, v31, s[40:41]
	v_cndmask_b32_e64 v29, v32, v30, s[38:39]
	v_pk_mul_f32 v[26:27], v[90:91], v[26:27]
	v_mov_b32_e32 v30, v195
	v_pk_fma_f32 v[22:23], v[94:95], v[22:23], v[26:27]
	v_pk_mul_f32 v[26:27], v[92:93], v[28:29]
	v_pk_fma_f32 v[14:15], v[14:15], v[98:99], v[22:23]
	v_pk_fma_f32 v[24:25], v[96:97], v[24:25], v[26:27]
	v_pk_add_f32 v[14:15], v[102:103], v[14:15]
	v_pk_fma_f32 v[16:17], v[16:17], v[100:101], v[24:25]
	v_pk_mul_f32 v[22:23], v[14:15], v[14:15]
	v_pk_add_f32 v[16:17], v[104:105], v[16:17]
	v_pk_fma_f32 v[22:23], v[22:23], s[78:79], 1.0 op_sel_hi:[1,0,0]
	v_pk_mul_f32 v[24:25], v[16:17], v[16:17]
	v_pk_mul_f32 v[22:23], v[14:15], v[22:23]
	v_pk_fma_f32 v[24:25], v[24:25], s[78:79], 1.0 op_sel_hi:[1,0,0]
	v_pk_mul_f32 v[22:23], v[22:23], s[24:25] op_sel_hi:[1,0]
	v_pk_mul_f32 v[24:25], v[16:17], v[24:25]
	v_exp_f32_e32 v22, v22
	v_exp_f32_e32 v23, v23
	v_pk_mul_f32 v[24:25], v[24:25], s[24:25] op_sel_hi:[1,0]
	v_mov_b32_e32 v31, v195
	v_exp_f32_e32 v24, v24
	v_exp_f32_e32 v25, v25
	v_mov_b32_e32 v32, v195
	v_mov_b32_e32 v33, v195
	v_mov_b32_dpp v30, v10 row_shr:1 row_mask:0xf bank_mask:0xf
	v_mov_b32_dpp v31, v10 row_shr:2 row_mask:0xf bank_mask:0xf
	v_mov_b32_dpp v32, v18 row_ror:1 row_mask:0xf bank_mask:0xf
	v_mov_b32_dpp v33, v18 row_ror:2 row_mask:0xf bank_mask:0xf
	v_cndmask_b32_e64 v18, v30, v32, s[40:41]
	v_cndmask_b32_e64 v30, v33, v31, s[38:39]
	v_mov_b32_e32 v31, v195
	v_mov_b32_e32 v32, v195
	v_mov_b32_e32 v33, v195
	v_mov_b32_e32 v34, v195
	v_pk_add_f32 v[22:23], v[22:23], 1.0 op_sel_hi:[1,0]
	v_mov_b32_dpp v31, v11 row_shr:1 row_mask:0xf bank_mask:0xf
	v_mov_b32_dpp v32, v11 row_shr:2 row_mask:0xf bank_mask:0xf
	v_mov_b32_dpp v33, v19 row_ror:1 row_mask:0xf bank_mask:0xf
	v_mov_b32_dpp v34, v19 row_ror:2 row_mask:0xf bank_mask:0xf
	v_rcp_f32_e32 v22, v22
	v_rcp_f32_e32 v23, v23
	v_pk_add_f32 v[24:25], v[24:25], 1.0 op_sel_hi:[1,0]
	v_cndmask_b32_e64 v19, v31, v33, s[40:41]
	v_cndmask_b32_e64 v31, v34, v32, s[38:39]
	v_mov_b32_e32 v32, v195
	v_mov_b32_e32 v33, v195
	v_mov_b32_e32 v34, v195
	v_mov_b32_e32 v35, v195
	v_rcp_f32_e32 v24, v24
	v_rcp_f32_e32 v25, v25
	v_mov_b32_dpp v32, v12 row_shr:1 row_mask:0xf bank_mask:0xf
	v_mov_b32_dpp v33, v12 row_shr:2 row_mask:0xf bank_mask:0xf
	v_mov_b32_dpp v34, v20 row_ror:1 row_mask:0xf bank_mask:0xf
	v_mov_b32_dpp v35, v20 row_ror:2 row_mask:0xf bank_mask:0xf
	v_cndmask_b32_e64 v20, v32, v34, s[40:41]
	v_cndmask_b32_e64 v32, v35, v33, s[38:39]
	v_mov_b32_e32 v33, v195
	v_mov_b32_e32 v34, v195
	v_mov_b32_e32 v35, v195
	v_mov_b32_e32 v36, v195
	v_mov_b32_dpp v33, v13 row_shr:1 row_mask:0xf bank_mask:0xf
	v_mov_b32_dpp v34, v13 row_shr:2 row_mask:0xf bank_mask:0xf
	v_mov_b32_dpp v35, v21 row_ror:1 row_mask:0xf bank_mask:0xf
	v_mov_b32_dpp v36, v21 row_ror:2 row_mask:0xf bank_mask:0xf
	v_pk_mul_f32 v[14:15], v[14:15], v[22:23]
	v_cndmask_b32_e64 v21, v33, v35, s[40:41]
	v_cndmask_b32_e64 v33, v36, v34, s[38:39]
	v_pk_mul_f32 v[6:7], v[6:7], v[14:15]
	v_pk_mul_f32 v[14:15], v[16:17], v[24:25]
	v_pk_mul_f32 v[16:17], v[66:67], v[30:31]
	v_pk_mul_f32 v[8:9], v[8:9], v[14:15]
	v_pk_fma_f32 v[16:17], v[70:71], v[18:19], v[16:17]
	v_pk_mul_f32 v[18:19], v[68:69], v[32:33]
	v_pk_fma_f32 v[10:11], v[10:11], v[74:75], v[16:17]
	v_pk_fma_f32 v[18:19], v[72:73], v[20:21], v[18:19]
	v_pk_add_f32 v[10:11], v[78:79], v[10:11]
	v_pk_fma_f32 v[12:13], v[12:13], v[76:77], v[18:19]
	v_pk_mul_f32 v[16:17], v[10:11], v[10:11]
	v_pk_add_f32 v[12:13], v[80:81], v[12:13]
	v_pk_fma_f32 v[16:17], v[16:17], s[78:79], 1.0 op_sel_hi:[1,0,0]
	v_pk_mul_f32 v[18:19], v[12:13], v[12:13]
	v_pk_mul_f32 v[16:17], v[10:11], v[16:17]
	v_pk_fma_f32 v[18:19], v[18:19], s[78:79], 1.0 op_sel_hi:[1,0,0]
	v_pk_mul_f32 v[16:17], v[16:17], s[24:25] op_sel_hi:[1,0]
	v_pk_mul_f32 v[18:19], v[12:13], v[18:19]
	v_exp_f32_e32 v16, v16
	v_exp_f32_e32 v17, v17
	v_pk_mul_f32 v[18:19], v[18:19], s[24:25] op_sel_hi:[1,0]
	v_pk_add_f32 v[16:17], v[16:17], 1.0 op_sel_hi:[1,0]
	v_exp_f32_e32 v18, v18
	v_exp_f32_e32 v19, v19
	v_rcp_f32_e32 v16, v16
	v_rcp_f32_e32 v17, v17
	v_pk_add_f32 v[18:19], v[18:19], 1.0 op_sel_hi:[1,0]
	s_nop 0
	v_rcp_f32_e32 v18, v18
	v_rcp_f32_e32 v19, v19
	v_pk_mul_f32 v[10:11], v[10:11], v[16:17]
	s_nop 0
	v_pk_mul_f32 v[10:11], v[2:3], v[10:11]
	v_pk_mul_f32 v[2:3], v[12:13], v[18:19]
	s_nop 0
	v_pk_mul_f32 v[12:13], v[4:5], v[2:3]
	v_cvt_pk_bf16_f32 v2, v6, v7
	v_add_u32_e32 v6, 0xb0, v210
	v_mad_i64_i32 v[6:7], s[8:9], v6, s7, v[42:43]
	v_lshl_add_u64 v[6:7], v[6:7], 0, v[138:139]
	v_cvt_pk_bf16_f32 v3, v8, v9
	v_cvt_pk_bf16_f32 v4, v10, v11
	v_cvt_pk_bf16_f32 v5, v12, v13
	global_store_dwordx4 v[6:7], v[2:5], off sc1
	s_cbranch_vccnz .LBB0_67
	s_and_b64 vcc, exec, s[46:47]
	s_cbranch_vccnz .LBB0_66
	s_barrier
	s_branch .LBB0_66

; __device__ __forceinline__ unsigned cvt_pk_bf16(float lo, float hi) { unsigned r; asm volatile("v_cvt_pk_bf16_f32 %0, %1, %2" : "=v"(r) : "v"(lo), "v"(hi)); return r; }
; template <class Epi>
; __device__ __forceinline__ void gemm_phase(LAS unsigned char* lds, const Gemm g, const Order& S, const Epi& E) {
;     ...
;                     for (int n = 0; n < 2; ++n) acc[a][b][m][n] = (f32x4){0.f, 0.f, 0.f, 0.f};
;     __device__ __forceinline__ void operator()(const f32x4 (&acc)[2][2][4][2], const Unit& u, int wr, int wc, int fr, int fq) const {
;     ...
;             for (int m = 0; m < 4; ++m) { bf16_t* rowp = base + (size_t)(row0 + ai * HALF + m * 16) * ld + col0;
; #pragma unroll
;                 for (int bj = 0; bj < 2; ++bj) { f32x4 v0 = acc[ai][bj][m][0] + bv[bj][0], v1 = acc[ai][bj][m][1] + bv[bj][1];
;                     if (sig) {
; #pragma unroll
;                         for (int j = 0; j < 4; ++j) { v0[j] = __builtin_amdgcn_rcpf(1.0f + __expf(-v0[j])); v1[j] = __builtin_amdgcn_rcpf(1.0f + __expf(-v1[j])); } }
;                     u32x4 w; w.x = cvt_pk_bf16(v0[0], v0[1]); w.y = cvt_pk_bf16(v0[2], v0[3]); w.z = cvt_pk_bf16(v1[0], v1[1]); w.w = cvt_pk_bf16(v1[2], v1[3]);
;                     *(u32x4*)(rowp + bj * HALF) = w; } }
.LBB0_283:
	v_lshlrev_b64 v[186:187], 11, v[216:217]
	v_lshl_add_u64 v[186:187], s[96:97], 0, v[186:187]
	s_andn2_b64 vcc, exec, s[30:31]
	v_lshl_add_u64 v[186:187], v[214:215], 1, v[186:187]
	s_cbranch_vccnz .LBB0_285
	v_cvt_pk_bf16_f32 v122, v226, v227
	v_cvt_pk_bf16_f32 v123, v190, v191
	v_cvt_pk_bf16_f32 v124, v224, v225
	v_cvt_pk_bf16_f32 v125, v192, v193
	v_mov_b32_e32 v126, 0
	global_store_dwordx4 v[186:187], v[122:125], off sc1
	v_mov_b32_e32 v127, v126
	v_mov_b32_e32 v128, v126
	v_mov_b32_e32 v129, v126
	v_mov_b32_e32 v122, v126
	v_mov_b32_e32 v123, v126
	v_mov_b32_e32 v124, v126
	v_mov_b32_e32 v125, v126

; __device__ __forceinline__ unsigned cvt_pk_bf16(float lo, float hi) { unsigned r; asm volatile("v_cvt_pk_bf16_f32 %0, %1, %2" : "=v"(r) : "v"(lo), "v"(hi)); return r; }
; template <class Epi>
; __device__ __forceinline__ void gemm_phase(LAS unsigned char* lds, const Gemm g, const Order& S, const Epi& E) {
;     ...
;                     for (int n = 0; n < 2; ++n) acc[a][b][m][n] = (f32x4){0.f, 0.f, 0.f, 0.f};
;     __device__ __forceinline__ void operator()(const f32x4 (&acc)[2][2][4][2], const Unit& u, int wr, int wc, int fr, int fq) const {
;     ...
;             for (int m = 0; m < 4; ++m) { bf16_t* rowp = base + (size_t)(row0 + ai * HALF + m * 16) * ld + col0;
; #pragma unroll
;                 for (int bj = 0; bj < 2; ++bj) { f32x4 v0 = acc[ai][bj][m][0] + bv[bj][0], v1 = acc[ai][bj][m][1] + bv[bj][1];
;                     if (sig) {
; #pragma unroll
;                         for (int j = 0; j < 4; ++j) { v0[j] = __builtin_amdgcn_rcpf(1.0f + __expf(-v0[j])); v1[j] = __builtin_amdgcn_rcpf(1.0f + __expf(-v1[j])); } }
;                     u32x4 w; w.x = cvt_pk_bf16(v0[0], v0[1]); w.y = cvt_pk_bf16(v0[2], v0[3]); w.z = cvt_pk_bf16(v1[0], v1[1]); w.w = cvt_pk_bf16(v1[2], v1[3]);
;                     *(u32x4*)(rowp + bj * HALF) = w; } }
.LBB0_287:
	s_andn2_b64 vcc, exec, s[30:31]
	s_cbranch_vccnz .LBB0_289
	v_cvt_pk_bf16_f32 v90, v190, v191
	v_cvt_pk_bf16_f32 v91, v182, v183
	v_cvt_pk_bf16_f32 v92, v188, v189
	v_cvt_pk_bf16_f32 v93, v184, v185
	v_mov_b32_e32 v94, 0
	global_store_dwordx4 v[186:187], v[90:93], off offset:256 sc1
	v_mov_b32_e32 v95, v94
	v_mov_b32_e32 v96, v94
	v_mov_b32_e32 v97, v94
	v_mov_b32_e32 v90, v94
	v_mov_b32_e32 v91, v94
	v_mov_b32_e32 v92, v94
	v_mov_b32_e32 v93, v94

; __device__ __forceinline__ unsigned cvt_pk_bf16(float lo, float hi) { unsigned r; asm volatile("v_cvt_pk_bf16_f32 %0, %1, %2" : "=v"(r) : "v"(lo), "v"(hi)); return r; }
; template <class Epi>
; __device__ __forceinline__ void gemm_phase(LAS unsigned char* lds, const Gemm g, const Order& S, const Epi& E) {
;     ...
;                     for (int n = 0; n < 2; ++n) acc[a][b][m][n] = (f32x4){0.f, 0.f, 0.f, 0.f};
;     __device__ __forceinline__ void operator()(const f32x4 (&acc)[2][2][4][2], const Unit& u, int wr, int wc, int fr, int fq) const {
;     ...
;             for (int m = 0; m < 4; ++m) { bf16_t* rowp = base + (size_t)(row0 + ai * HALF + m * 16) * ld + col0;
; #pragma unroll
;                 for (int bj = 0; bj < 2; ++bj) { f32x4 v0 = acc[ai][bj][m][0] + bv[bj][0], v1 = acc[ai][bj][m][1] + bv[bj][1];
;                     if (sig) {
; #pragma unroll
;                         for (int j = 0; j < 4; ++j) { v0[j] = __builtin_amdgcn_rcpf(1.0f + __expf(-v0[j])); v1[j] = __builtin_amdgcn_rcpf(1.0f + __expf(-v1[j])); } }
;                     u32x4 w; w.x = cvt_pk_bf16(v0[0], v0[1]); w.y = cvt_pk_bf16(v0[2], v0[3]); w.z = cvt_pk_bf16(v1[0], v1[1]); w.w = cvt_pk_bf16(v1[2], v1[3]);
;                     *(u32x4*)(rowp + bj * HALF) = w; } }
.LBB0_291:
	v_ashrrev_i32_e32 v223, 31, v222
	v_lshlrev_b64 v[170:171], 11, v[222:223]
	v_lshl_add_u64 v[170:171], s[96:97], 0, v[170:171]
	s_andn2_b64 vcc, exec, s[30:31]
	v_lshl_add_u64 v[170:171], v[214:215], 1, v[170:171]
	s_cbranch_vccnz .LBB0_293
	v_cvt_pk_bf16_f32 v114, v180, v181
	v_cvt_pk_bf16_f32 v115, v174, v175
	v_cvt_pk_bf16_f32 v116, v178, v179
	v_cvt_pk_bf16_f32 v117, v176, v177
	v_mov_b32_e32 v118, 0
	global_store_dwordx4 v[170:171], v[114:117], off sc1
	v_mov_b32_e32 v119, v118
	v_mov_b32_e32 v120, v118
	v_mov_b32_e32 v121, v118
	v_mov_b32_e32 v114, v118
	v_mov_b32_e32 v115, v118
	v_mov_b32_e32 v116, v118
	v_mov_b32_e32 v117, v118

; __device__ __forceinline__ unsigned cvt_pk_bf16(float lo, float hi) { unsigned r; asm volatile("v_cvt_pk_bf16_f32 %0, %1, %2" : "=v"(r) : "v"(lo), "v"(hi)); return r; }
; template <class Epi>
; __device__ __forceinline__ void gemm_phase(LAS unsigned char* lds, const Gemm g, const Order& S, const Epi& E) {
;     ...
;                     for (int n = 0; n < 2; ++n) acc[a][b][m][n] = (f32x4){0.f, 0.f, 0.f, 0.f};
;     __device__ __forceinline__ void operator()(const f32x4 (&acc)[2][2][4][2], const Unit& u, int wr, int wc, int fr, int fq) const {
;     ...
;             for (int m = 0; m < 4; ++m) { bf16_t* rowp = base + (size_t)(row0 + ai * HALF + m * 16) * ld + col0;
; #pragma unroll
;                 for (int bj = 0; bj < 2; ++bj) { f32x4 v0 = acc[ai][bj][m][0] + bv[bj][0], v1 = acc[ai][bj][m][1] + bv[bj][1];
;                     if (sig) {
; #pragma unroll
;                         for (int j = 0; j < 4; ++j) { v0[j] = __builtin_amdgcn_rcpf(1.0f + __expf(-v0[j])); v1[j] = __builtin_amdgcn_rcpf(1.0f + __expf(-v1[j])); } }
;                     u32x4 w; w.x = cvt_pk_bf16(v0[0], v0[1]); w.y = cvt_pk_bf16(v0[2], v0[3]); w.z = cvt_pk_bf16(v1[0], v1[1]); w.w = cvt_pk_bf16(v1[2], v1[3]);
;                     *(u32x4*)(rowp + bj * HALF) = w; } }
.LBB0_295:
	s_andn2_b64 vcc, exec, s[30:31]
	s_cbranch_vccnz .LBB0_297
	v_cvt_pk_bf16_f32 v82, v174, v175
	v_cvt_pk_bf16_f32 v83, v166, v167
	v_cvt_pk_bf16_f32 v84, v172, v173
	v_cvt_pk_bf16_f32 v85, v168, v169
	v_mov_b32_e32 v86, 0
	global_store_dwordx4 v[170:171], v[82:85], off offset:256 sc1
	v_mov_b32_e32 v87, v86
	v_mov_b32_e32 v88, v86
	v_mov_b32_e32 v89, v86
	v_mov_b32_e32 v82, v86
	v_mov_b32_e32 v83, v86
	v_mov_b32_e32 v84, v86
	v_mov_b32_e32 v85, v86

; __device__ __forceinline__ unsigned cvt_pk_bf16(float lo, float hi) { unsigned r; asm volatile("v_cvt_pk_bf16_f32 %0, %1, %2" : "=v"(r) : "v"(lo), "v"(hi)); return r; }
; template <class Epi>
; __device__ __forceinline__ void gemm_phase(LAS unsigned char* lds, const Gemm g, const Order& S, const Epi& E) {
;     ...
;                     for (int n = 0; n < 2; ++n) acc[a][b][m][n] = (f32x4){0.f, 0.f, 0.f, 0.f};
;     __device__ __forceinline__ void operator()(const f32x4 (&acc)[2][2][4][2], const Unit& u, int wr, int wc, int fr, int fq) const {
;     ...
;             for (int m = 0; m < 4; ++m) { bf16_t* rowp = base + (size_t)(row0 + ai * HALF + m * 16) * ld + col0;
; #pragma unroll
;                 for (int bj = 0; bj < 2; ++bj) { f32x4 v0 = acc[ai][bj][m][0] + bv[bj][0], v1 = acc[ai][bj][m][1] + bv[bj][1];
;                     if (sig) {
; #pragma unroll
;                         for (int j = 0; j < 4; ++j) { v0[j] = __builtin_amdgcn_rcpf(1.0f + __expf(-v0[j])); v1[j] = __builtin_amdgcn_rcpf(1.0f + __expf(-v1[j])); } }
;                     u32x4 w; w.x = cvt_pk_bf16(v0[0], v0[1]); w.y = cvt_pk_bf16(v0[2], v0[3]); w.z = cvt_pk_bf16(v1[0], v1[1]); w.w = cvt_pk_bf16(v1[2], v1[3]);
;                     *(u32x4*)(rowp + bj * HALF) = w; } }
.LBB0_299:
	v_ashrrev_i32_e32 v221, 31, v220
	v_lshlrev_b64 v[154:155], 11, v[220:221]
	v_lshl_add_u64 v[154:155], s[96:97], 0, v[154:155]
	s_andn2_b64 vcc, exec, s[30:31]
	v_lshl_add_u64 v[154:155], v[214:215], 1, v[154:155]
	s_cbranch_vccnz .LBB0_301
	v_cvt_pk_bf16_f32 v106, v164, v165
	v_cvt_pk_bf16_f32 v107, v158, v159
	v_cvt_pk_bf16_f32 v108, v162, v163
	v_cvt_pk_bf16_f32 v109, v160, v161
	v_mov_b32_e32 v110, 0
	global_store_dwordx4 v[154:155], v[106:109], off sc1
	v_mov_b32_e32 v111, v110
	v_mov_b32_e32 v112, v110
	v_mov_b32_e32 v113, v110
	v_mov_b32_e32 v106, v110
	v_mov_b32_e32 v107, v110
	v_mov_b32_e32 v108, v110
	v_mov_b32_e32 v109, v110

; __device__ __forceinline__ unsigned cvt_pk_bf16(float lo, float hi) { unsigned r; asm volatile("v_cvt_pk_bf16_f32 %0, %1, %2" : "=v"(r) : "v"(lo), "v"(hi)); return r; }
; template <class Epi>
; __device__ __forceinline__ void gemm_phase(LAS unsigned char* lds, const Gemm g, const Order& S, const Epi& E) {
;     ...
;                     for (int n = 0; n < 2; ++n) acc[a][b][m][n] = (f32x4){0.f, 0.f, 0.f, 0.f};
;     __device__ __forceinline__ void operator()(const f32x4 (&acc)[2][2][4][2], const Unit& u, int wr, int wc, int fr, int fq) const {
;     ...
;             for (int m = 0; m < 4; ++m) { bf16_t* rowp = base + (size_t)(row0 + ai * HALF + m * 16) * ld + col0;
; #pragma unroll
;                 for (int bj = 0; bj < 2; ++bj) { f32x4 v0 = acc[ai][bj][m][0] + bv[bj][0], v1 = acc[ai][bj][m][1] + bv[bj][1];
;                     if (sig) {
; #pragma unroll
;                         for (int j = 0; j < 4; ++j) { v0[j] = __builtin_amdgcn_rcpf(1.0f + __expf(-v0[j])); v1[j] = __builtin_amdgcn_rcpf(1.0f + __expf(-v1[j])); } }
;                     u32x4 w; w.x = cvt_pk_bf16(v0[0], v0[1]); w.y = cvt_pk_bf16(v0[2], v0[3]); w.z = cvt_pk_bf16(v1[0], v1[1]); w.w = cvt_pk_bf16(v1[2], v1[3]);
;                     *(u32x4*)(rowp + bj * HALF) = w; } }
.LBB0_303:
	s_andn2_b64 vcc, exec, s[30:31]
	s_cbranch_vccnz .LBB0_305
	v_cvt_pk_bf16_f32 v74, v158, v159
	v_cvt_pk_bf16_f32 v75, v150, v151
	v_cvt_pk_bf16_f32 v76, v156, v157
	v_cvt_pk_bf16_f32 v77, v152, v153
	v_mov_b32_e32 v78, 0
	global_store_dwordx4 v[154:155], v[74:77], off offset:256 sc1
	v_mov_b32_e32 v79, v78
	v_mov_b32_e32 v80, v78
	v_mov_b32_e32 v81, v78
	v_mov_b32_e32 v74, v78
	v_mov_b32_e32 v75, v78
	v_mov_b32_e32 v76, v78
	v_mov_b32_e32 v77, v78

; __device__ __forceinline__ unsigned cvt_pk_bf16(float lo, float hi) { unsigned r; asm volatile("v_cvt_pk_bf16_f32 %0, %1, %2" : "=v"(r) : "v"(lo), "v"(hi)); return r; }
; template <class Epi>
; __device__ __forceinline__ void gemm_phase(LAS unsigned char* lds, const Gemm g, const Order& S, const Epi& E) {
;     ...
;                     for (int n = 0; n < 2; ++n) acc[a][b][m][n] = (f32x4){0.f, 0.f, 0.f, 0.f};
;     __device__ __forceinline__ void operator()(const f32x4 (&acc)[2][2][4][2], const Unit& u, int wr, int wc, int fr, int fq) const {
;     ...
;             for (int m = 0; m < 4; ++m) { bf16_t* rowp = base + (size_t)(row0 + ai * HALF + m * 16) * ld + col0;
; #pragma unroll
;                 for (int bj = 0; bj < 2; ++bj) { f32x4 v0 = acc[ai][bj][m][0] + bv[bj][0], v1 = acc[ai][bj][m][1] + bv[bj][1];
;                     if (sig) {
; #pragma unroll
;                         for (int j = 0; j < 4; ++j) { v0[j] = __builtin_amdgcn_rcpf(1.0f + __expf(-v0[j])); v1[j] = __builtin_amdgcn_rcpf(1.0f + __expf(-v1[j])); } }
;                     u32x4 w; w.x = cvt_pk_bf16(v0[0], v0[1]); w.y = cvt_pk_bf16(v0[2], v0[3]); w.z = cvt_pk_bf16(v1[0], v1[1]); w.w = cvt_pk_bf16(v1[2], v1[3]);
;                     *(u32x4*)(rowp + bj * HALF) = w; } }
.LBB0_307:
	v_ashrrev_i32_e32 v219, 31, v218
	v_lshlrev_b64 v[138:139], 11, v[218:219]
	v_lshl_add_u64 v[138:139], s[96:97], 0, v[138:139]
	s_andn2_b64 vcc, exec, s[30:31]
	v_lshl_add_u64 v[138:139], v[214:215], 1, v[138:139]
	s_cbranch_vccnz .LBB0_309
	v_cvt_pk_bf16_f32 v98, v148, v149
	v_cvt_pk_bf16_f32 v99, v142, v143
	v_cvt_pk_bf16_f32 v100, v146, v147
	v_cvt_pk_bf16_f32 v101, v144, v145
	v_mov_b32_e32 v102, 0
	global_store_dwordx4 v[138:139], v[98:101], off sc1
	v_mov_b32_e32 v103, v102
	v_mov_b32_e32 v104, v102
	v_mov_b32_e32 v105, v102
	v_mov_b32_e32 v98, v102
	v_mov_b32_e32 v99, v102
	v_mov_b32_e32 v100, v102
	v_mov_b32_e32 v101, v102

; __device__ __forceinline__ unsigned cvt_pk_bf16(float lo, float hi) { unsigned r; asm volatile("v_cvt_pk_bf16_f32 %0, %1, %2" : "=v"(r) : "v"(lo), "v"(hi)); return r; }
; template <class Epi>
; __device__ __forceinline__ void gemm_phase(LAS unsigned char* lds, const Gemm g, const Order& S, const Epi& E) {
;     ...
;                     for (int n = 0; n < 2; ++n) acc[a][b][m][n] = (f32x4){0.f, 0.f, 0.f, 0.f};
;     __device__ __forceinline__ void operator()(const f32x4 (&acc)[2][2][4][2], const Unit& u, int wr, int wc, int fr, int fq) const {
;     ...
;             for (int m = 0; m < 4; ++m) { bf16_t* rowp = base + (size_t)(row0 + ai * HALF + m * 16) * ld + col0;
; #pragma unroll
;                 for (int bj = 0; bj < 2; ++bj) { f32x4 v0 = acc[ai][bj][m][0] + bv[bj][0], v1 = acc[ai][bj][m][1] + bv[bj][1];
;                     if (sig) {
; #pragma unroll
;                         for (int j = 0; j < 4; ++j) { v0[j] = __builtin_amdgcn_rcpf(1.0f + __expf(-v0[j])); v1[j] = __builtin_amdgcn_rcpf(1.0f + __expf(-v1[j])); } }
;                     u32x4 w; w.x = cvt_pk_bf16(v0[0], v0[1]); w.y = cvt_pk_bf16(v0[2], v0[3]); w.z = cvt_pk_bf16(v1[0], v1[1]); w.w = cvt_pk_bf16(v1[2], v1[3]);
;                     *(u32x4*)(rowp + bj * HALF) = w; } }
.LBB0_311:
	s_andn2_b64 vcc, exec, s[30:31]
	s_cbranch_vccnz .LBB0_313
	v_cvt_pk_bf16_f32 v66, v142, v143
	v_cvt_pk_bf16_f32 v67, v134, v135
	v_cvt_pk_bf16_f32 v68, v140, v141
	v_cvt_pk_bf16_f32 v69, v136, v137
	v_mov_b32_e32 v70, 0
	global_store_dwordx4 v[138:139], v[66:69], off offset:256 sc1
	v_mov_b32_e32 v71, v70
	v_mov_b32_e32 v72, v70
	v_mov_b32_e32 v73, v70
	v_mov_b32_e32 v66, v70
	v_mov_b32_e32 v67, v70
	v_mov_b32_e32 v68, v70
	v_mov_b32_e32 v69, v70

; __device__ __forceinline__ unsigned cvt_pk_bf16(float lo, float hi) { unsigned r; asm volatile("v_cvt_pk_bf16_f32 %0, %1, %2" : "=v"(r) : "v"(lo), "v"(hi)); return r; }
; template <class Epi>
; __device__ __forceinline__ void gemm_phase(LAS unsigned char* lds, const Gemm g, const Order& S, const Epi& E) {
;     ...
;                     for (int n = 0; n < 2; ++n) acc[a][b][m][n] = (f32x4){0.f, 0.f, 0.f, 0.f};
;     __device__ __forceinline__ void operator()(const f32x4 (&acc)[2][2][4][2], const Unit& u, int wr, int wc, int fr, int fq) const {
;     ...
;             for (int m = 0; m < 4; ++m) { bf16_t* rowp = base + (size_t)(row0 + ai * HALF + m * 16) * ld + col0;
; #pragma unroll
;                 for (int bj = 0; bj < 2; ++bj) { f32x4 v0 = acc[ai][bj][m][0] + bv[bj][0], v1 = acc[ai][bj][m][1] + bv[bj][1];
;                     if (sig) {
; #pragma unroll
;                         for (int j = 0; j < 4; ++j) { v0[j] = __builtin_amdgcn_rcpf(1.0f + __expf(-v0[j])); v1[j] = __builtin_amdgcn_rcpf(1.0f + __expf(-v1[j])); } }
;                     u32x4 w; w.x = cvt_pk_bf16(v0[0], v0[1]); w.y = cvt_pk_bf16(v0[2], v0[3]); w.z = cvt_pk_bf16(v1[0], v1[1]); w.w = cvt_pk_bf16(v1[2], v1[3]);
;                     *(u32x4*)(rowp + bj * HALF) = w; } }
.LBB0_331:
	v_ashrrev_i32_e32 v223, 31, v222
	v_lshlrev_b64 v[186:187], 11, v[222:223]
	v_lshl_add_u64 v[186:187], s[96:97], 0, v[186:187]
	s_andn2_b64 vcc, exec, s[0:1]
	v_lshl_add_u64 v[186:187], v[214:215], 1, v[186:187]
	s_cbranch_vccnz .LBB0_333
	v_cvt_pk_bf16_f32 v58, v226, v227
	v_cvt_pk_bf16_f32 v59, v190, v191
	v_cvt_pk_bf16_f32 v60, v224, v225
	v_cvt_pk_bf16_f32 v61, v192, v193
	v_mov_b32_e32 v62, 0
	global_store_dwordx4 v[186:187], v[58:61], off sc1
	v_mov_b32_e32 v63, v62
	v_mov_b32_e32 v64, v62
	v_mov_b32_e32 v65, v62
	v_mov_b32_e32 v58, v62
	v_mov_b32_e32 v59, v62
	v_mov_b32_e32 v60, v62
	v_mov_b32_e32 v61, v62

; __device__ __forceinline__ unsigned cvt_pk_bf16(float lo, float hi) { unsigned r; asm volatile("v_cvt_pk_bf16_f32 %0, %1, %2" : "=v"(r) : "v"(lo), "v"(hi)); return r; }
; template <class Epi>
; __device__ __forceinline__ void gemm_phase(LAS unsigned char* lds, const Gemm g, const Order& S, const Epi& E) {
;     ...
;                     for (int n = 0; n < 2; ++n) acc[a][b][m][n] = (f32x4){0.f, 0.f, 0.f, 0.f};
;     __device__ __forceinline__ void operator()(const f32x4 (&acc)[2][2][4][2], const Unit& u, int wr, int wc, int fr, int fq) const {
;     ...
;             for (int m = 0; m < 4; ++m) { bf16_t* rowp = base + (size_t)(row0 + ai * HALF + m * 16) * ld + col0;
; #pragma unroll
;                 for (int bj = 0; bj < 2; ++bj) { f32x4 v0 = acc[ai][bj][m][0] + bv[bj][0], v1 = acc[ai][bj][m][1] + bv[bj][1];
;                     if (sig) {
; #pragma unroll
;                         for (int j = 0; j < 4; ++j) { v0[j] = __builtin_amdgcn_rcpf(1.0f + __expf(-v0[j])); v1[j] = __builtin_amdgcn_rcpf(1.0f + __expf(-v1[j])); } }
;                     u32x4 w; w.x = cvt_pk_bf16(v0[0], v0[1]); w.y = cvt_pk_bf16(v0[2], v0[3]); w.z = cvt_pk_bf16(v1[0], v1[1]); w.w = cvt_pk_bf16(v1[2], v1[3]);
;                     *(u32x4*)(rowp + bj * HALF) = w; } }
.LBB0_335:
	s_andn2_b64 vcc, exec, s[0:1]
	s_cbranch_vccnz .LBB0_337
	v_cvt_pk_bf16_f32 v26, v190, v191
	v_cvt_pk_bf16_f32 v27, v182, v183
	v_cvt_pk_bf16_f32 v28, v188, v189
	v_cvt_pk_bf16_f32 v29, v184, v185
	v_mov_b32_e32 v30, 0
	global_store_dwordx4 v[186:187], v[26:29], off offset:256 sc1
	v_mov_b32_e32 v31, v30
	v_mov_b32_e32 v32, v30
	v_mov_b32_e32 v33, v30
	v_mov_b32_e32 v26, v30
	v_mov_b32_e32 v27, v30
	v_mov_b32_e32 v28, v30
	v_mov_b32_e32 v29, v30

; __device__ __forceinline__ unsigned cvt_pk_bf16(float lo, float hi) { unsigned r; asm volatile("v_cvt_pk_bf16_f32 %0, %1, %2" : "=v"(r) : "v"(lo), "v"(hi)); return r; }
; template <class Epi>
; __device__ __forceinline__ void gemm_phase(LAS unsigned char* lds, const Gemm g, const Order& S, const Epi& E) {
;     ...
;                     for (int n = 0; n < 2; ++n) acc[a][b][m][n] = (f32x4){0.f, 0.f, 0.f, 0.f};
;     __device__ __forceinline__ void operator()(const f32x4 (&acc)[2][2][4][2], const Unit& u, int wr, int wc, int fr, int fq) const {
;     ...
;             for (int m = 0; m < 4; ++m) { bf16_t* rowp = base + (size_t)(row0 + ai * HALF + m * 16) * ld + col0;
; #pragma unroll
;                 for (int bj = 0; bj < 2; ++bj) { f32x4 v0 = acc[ai][bj][m][0] + bv[bj][0], v1 = acc[ai][bj][m][1] + bv[bj][1];
;                     if (sig) {
; #pragma unroll
;                         for (int j = 0; j < 4; ++j) { v0[j] = __builtin_amdgcn_rcpf(1.0f + __expf(-v0[j])); v1[j] = __builtin_amdgcn_rcpf(1.0f + __expf(-v1[j])); } }
;                     u32x4 w; w.x = cvt_pk_bf16(v0[0], v0[1]); w.y = cvt_pk_bf16(v0[2], v0[3]); w.z = cvt_pk_bf16(v1[0], v1[1]); w.w = cvt_pk_bf16(v1[2], v1[3]);
;                     *(u32x4*)(rowp + bj * HALF) = w; } }
.LBB0_339:
	v_ashrrev_i32_e32 v221, 31, v220
	v_lshlrev_b64 v[170:171], 11, v[220:221]
	v_lshl_add_u64 v[170:171], s[96:97], 0, v[170:171]
	s_andn2_b64 vcc, exec, s[0:1]
	v_lshl_add_u64 v[170:171], v[214:215], 1, v[170:171]
	s_cbranch_vccnz .LBB0_341
	v_cvt_pk_bf16_f32 v50, v180, v181
	v_cvt_pk_bf16_f32 v51, v174, v175
	v_cvt_pk_bf16_f32 v52, v178, v179
	v_cvt_pk_bf16_f32 v53, v176, v177
	v_mov_b32_e32 v54, 0
	global_store_dwordx4 v[170:171], v[50:53], off sc1
	v_mov_b32_e32 v55, v54
	v_mov_b32_e32 v56, v54
	v_mov_b32_e32 v57, v54
	v_mov_b32_e32 v50, v54
	v_mov_b32_e32 v51, v54
	v_mov_b32_e32 v52, v54
	v_mov_b32_e32 v53, v54

; __device__ __forceinline__ unsigned cvt_pk_bf16(float lo, float hi) { unsigned r; asm volatile("v_cvt_pk_bf16_f32 %0, %1, %2" : "=v"(r) : "v"(lo), "v"(hi)); return r; }
; template <class Epi>
; __device__ __forceinline__ void gemm_phase(LAS unsigned char* lds, const Gemm g, const Order& S, const Epi& E) {
;     ...
;                     for (int n = 0; n < 2; ++n) acc[a][b][m][n] = (f32x4){0.f, 0.f, 0.f, 0.f};
;     __device__ __forceinline__ void operator()(const f32x4 (&acc)[2][2][4][2], const Unit& u, int wr, int wc, int fr, int fq) const {
;     ...
;             for (int m = 0; m < 4; ++m) { bf16_t* rowp = base + (size_t)(row0 + ai * HALF + m * 16) * ld + col0;
; #pragma unroll
;                 for (int bj = 0; bj < 2; ++bj) { f32x4 v0 = acc[ai][bj][m][0] + bv[bj][0], v1 = acc[ai][bj][m][1] + bv[bj][1];
;                     if (sig) {
; #pragma unroll
;                         for (int j = 0; j < 4; ++j) { v0[j] = __builtin_amdgcn_rcpf(1.0f + __expf(-v0[j])); v1[j] = __builtin_amdgcn_rcpf(1.0f + __expf(-v1[j])); } }
;                     u32x4 w; w.x = cvt_pk_bf16(v0[0], v0[1]); w.y = cvt_pk_bf16(v0[2], v0[3]); w.z = cvt_pk_bf16(v1[0], v1[1]); w.w = cvt_pk_bf16(v1[2], v1[3]);
;                     *(u32x4*)(rowp + bj * HALF) = w; } }
.LBB0_343:
	s_andn2_b64 vcc, exec, s[0:1]
	s_cbranch_vccnz .LBB0_345
	v_cvt_pk_bf16_f32 v18, v174, v175
	v_cvt_pk_bf16_f32 v19, v166, v167
	v_cvt_pk_bf16_f32 v20, v172, v173
	v_cvt_pk_bf16_f32 v21, v168, v169
	v_mov_b32_e32 v22, 0
	global_store_dwordx4 v[170:171], v[18:21], off offset:256 sc1
	v_mov_b32_e32 v23, v22
	v_mov_b32_e32 v24, v22
	v_mov_b32_e32 v25, v22
	v_mov_b32_e32 v18, v22
	v_mov_b32_e32 v19, v22
	v_mov_b32_e32 v20, v22
	v_mov_b32_e32 v21, v22

; __device__ __forceinline__ unsigned cvt_pk_bf16(float lo, float hi) { unsigned r; asm volatile("v_cvt_pk_bf16_f32 %0, %1, %2" : "=v"(r) : "v"(lo), "v"(hi)); return r; }
; template <class Epi>
; __device__ __forceinline__ void gemm_phase(LAS unsigned char* lds, const Gemm g, const Order& S, const Epi& E) {
;     ...
;                     for (int n = 0; n < 2; ++n) acc[a][b][m][n] = (f32x4){0.f, 0.f, 0.f, 0.f};
;     __device__ __forceinline__ void operator()(const f32x4 (&acc)[2][2][4][2], const Unit& u, int wr, int wc, int fr, int fq) const {
;     ...
;             for (int m = 0; m < 4; ++m) { bf16_t* rowp = base + (size_t)(row0 + ai * HALF + m * 16) * ld + col0;
; #pragma unroll
;                 for (int bj = 0; bj < 2; ++bj) { f32x4 v0 = acc[ai][bj][m][0] + bv[bj][0], v1 = acc[ai][bj][m][1] + bv[bj][1];
;                     if (sig) {
; #pragma unroll
;                         for (int j = 0; j < 4; ++j) { v0[j] = __builtin_amdgcn_rcpf(1.0f + __expf(-v0[j])); v1[j] = __builtin_amdgcn_rcpf(1.0f + __expf(-v1[j])); } }
;                     u32x4 w; w.x = cvt_pk_bf16(v0[0], v0[1]); w.y = cvt_pk_bf16(v0[2], v0[3]); w.z = cvt_pk_bf16(v1[0], v1[1]); w.w = cvt_pk_bf16(v1[2], v1[3]);
;                     *(u32x4*)(rowp + bj * HALF) = w; } }
.LBB0_347:
	v_ashrrev_i32_e32 v219, 31, v218
	v_lshlrev_b64 v[154:155], 11, v[218:219]
	v_lshl_add_u64 v[154:155], s[96:97], 0, v[154:155]
	s_andn2_b64 vcc, exec, s[0:1]
	v_lshl_add_u64 v[154:155], v[214:215], 1, v[154:155]
	s_cbranch_vccnz .LBB0_349
	v_cvt_pk_bf16_f32 v42, v164, v165
	v_cvt_pk_bf16_f32 v43, v158, v159
	v_cvt_pk_bf16_f32 v44, v162, v163
	v_cvt_pk_bf16_f32 v45, v160, v161
	v_mov_b32_e32 v46, 0
	global_store_dwordx4 v[154:155], v[42:45], off sc1
	v_mov_b32_e32 v47, v46
	v_mov_b32_e32 v48, v46
	v_mov_b32_e32 v49, v46
	v_mov_b32_e32 v42, v46
	v_mov_b32_e32 v43, v46
	v_mov_b32_e32 v44, v46
	v_mov_b32_e32 v45, v46

; __device__ __forceinline__ unsigned cvt_pk_bf16(float lo, float hi) { unsigned r; asm volatile("v_cvt_pk_bf16_f32 %0, %1, %2" : "=v"(r) : "v"(lo), "v"(hi)); return r; }
; template <class Epi>
; __device__ __forceinline__ void gemm_phase(LAS unsigned char* lds, const Gemm g, const Order& S, const Epi& E) {
;     ...
;                     for (int n = 0; n < 2; ++n) acc[a][b][m][n] = (f32x4){0.f, 0.f, 0.f, 0.f};
;     __device__ __forceinline__ void operator()(const f32x4 (&acc)[2][2][4][2], const Unit& u, int wr, int wc, int fr, int fq) const {
;     ...
;             for (int m = 0; m < 4; ++m) { bf16_t* rowp = base + (size_t)(row0 + ai * HALF + m * 16) * ld + col0;
; #pragma unroll
;                 for (int bj = 0; bj < 2; ++bj) { f32x4 v0 = acc[ai][bj][m][0] + bv[bj][0], v1 = acc[ai][bj][m][1] + bv[bj][1];
;                     if (sig) {
; #pragma unroll
;                         for (int j = 0; j < 4; ++j) { v0[j] = __builtin_amdgcn_rcpf(1.0f + __expf(-v0[j])); v1[j] = __builtin_amdgcn_rcpf(1.0f + __expf(-v1[j])); } }
;                     u32x4 w; w.x = cvt_pk_bf16(v0[0], v0[1]); w.y = cvt_pk_bf16(v0[2], v0[3]); w.z = cvt_pk_bf16(v1[0], v1[1]); w.w = cvt_pk_bf16(v1[2], v1[3]);
;                     *(u32x4*)(rowp + bj * HALF) = w; } }
.LBB0_351:
	s_andn2_b64 vcc, exec, s[0:1]
	s_cbranch_vccnz .LBB0_353
	v_cvt_pk_bf16_f32 v10, v158, v159
	v_cvt_pk_bf16_f32 v11, v150, v151
	v_cvt_pk_bf16_f32 v12, v156, v157
	v_cvt_pk_bf16_f32 v13, v152, v153
	v_mov_b32_e32 v14, 0
	global_store_dwordx4 v[154:155], v[10:13], off offset:256 sc1
	v_mov_b32_e32 v15, v14
	v_mov_b32_e32 v16, v14
	v_mov_b32_e32 v17, v14
	v_mov_b32_e32 v10, v14
	v_mov_b32_e32 v11, v14
	v_mov_b32_e32 v12, v14
	v_mov_b32_e32 v13, v14

; __device__ __forceinline__ unsigned cvt_pk_bf16(float lo, float hi) { unsigned r; asm volatile("v_cvt_pk_bf16_f32 %0, %1, %2" : "=v"(r) : "v"(lo), "v"(hi)); return r; }
; template <class Epi>
; __device__ __forceinline__ void gemm_phase(LAS unsigned char* lds, const Gemm g, const Order& S, const Epi& E) {
;     ...
;                     for (int n = 0; n < 2; ++n) acc[a][b][m][n] = (f32x4){0.f, 0.f, 0.f, 0.f};
;     __device__ __forceinline__ void operator()(const f32x4 (&acc)[2][2][4][2], const Unit& u, int wr, int wc, int fr, int fq) const {
;     ...
;             for (int m = 0; m < 4; ++m) { bf16_t* rowp = base + (size_t)(row0 + ai * HALF + m * 16) * ld + col0;
; #pragma unroll
;                 for (int bj = 0; bj < 2; ++bj) { f32x4 v0 = acc[ai][bj][m][0] + bv[bj][0], v1 = acc[ai][bj][m][1] + bv[bj][1];
;                     if (sig) {
; #pragma unroll
;                         for (int j = 0; j < 4; ++j) { v0[j] = __builtin_amdgcn_rcpf(1.0f + __expf(-v0[j])); v1[j] = __builtin_amdgcn_rcpf(1.0f + __expf(-v1[j])); } }
;                     u32x4 w; w.x = cvt_pk_bf16(v0[0], v0[1]); w.y = cvt_pk_bf16(v0[2], v0[3]); w.z = cvt_pk_bf16(v1[0], v1[1]); w.w = cvt_pk_bf16(v1[2], v1[3]);
;                     *(u32x4*)(rowp + bj * HALF) = w; } }
.LBB0_355:
	v_ashrrev_i32_e32 v217, 31, v216
	v_lshlrev_b64 v[138:139], 11, v[216:217]
	v_lshl_add_u64 v[138:139], s[96:97], 0, v[138:139]
	s_andn2_b64 vcc, exec, s[0:1]
	v_lshl_add_u64 v[138:139], v[214:215], 1, v[138:139]
	s_cbranch_vccnz .LBB0_357
	v_cvt_pk_bf16_f32 v34, v148, v149
	v_cvt_pk_bf16_f32 v35, v142, v143
	v_cvt_pk_bf16_f32 v36, v146, v147
	v_cvt_pk_bf16_f32 v37, v144, v145
	v_mov_b32_e32 v38, 0
	global_store_dwordx4 v[138:139], v[34:37], off sc1
	v_mov_b32_e32 v39, v38
	v_mov_b32_e32 v40, v38
	v_mov_b32_e32 v41, v38
	v_mov_b32_e32 v34, v38
	v_mov_b32_e32 v35, v38
	v_mov_b32_e32 v36, v38
	v_mov_b32_e32 v37, v38

; __device__ __forceinline__ unsigned cvt_pk_bf16(float lo, float hi) { unsigned r; asm volatile("v_cvt_pk_bf16_f32 %0, %1, %2" : "=v"(r) : "v"(lo), "v"(hi)); return r; }
; template <class Epi>
; __device__ __forceinline__ void gemm_phase(LAS unsigned char* lds, const Gemm g, const Order& S, const Epi& E) {
;     ...
;                     for (int n = 0; n < 2; ++n) acc[a][b][m][n] = (f32x4){0.f, 0.f, 0.f, 0.f};
;         }
;         cur = nxt; cA = nA; cB = nB; ++ui;
;     __device__ __forceinline__ void operator()(const f32x4 (&acc)[2][2][4][2], const Unit& u, int wr, int wc, int fr, int fq) const {
;     ...
;             for (int m = 0; m < 4; ++m) { bf16_t* rowp = base + (size_t)(row0 + ai * HALF + m * 16) * ld + col0;
; #pragma unroll
;                 for (int bj = 0; bj < 2; ++bj) { f32x4 v0 = acc[ai][bj][m][0] + bv[bj][0], v1 = acc[ai][bj][m][1] + bv[bj][1];
;                     if (sig) {
; #pragma unroll
;                         for (int j = 0; j < 4; ++j) { v0[j] = __builtin_amdgcn_rcpf(1.0f + __expf(-v0[j])); v1[j] = __builtin_amdgcn_rcpf(1.0f + __expf(-v1[j])); } }
;                     u32x4 w; w.x = cvt_pk_bf16(v0[0], v0[1]); w.y = cvt_pk_bf16(v0[2], v0[3]); w.z = cvt_pk_bf16(v1[0], v1[1]); w.w = cvt_pk_bf16(v1[2], v1[3]);
;                     *(u32x4*)(rowp + bj * HALF) = w; } }
.LBB0_361:
	v_cvt_pk_bf16_f32 v2, v142, v143
	v_cvt_pk_bf16_f32 v3, v134, v135
	v_cvt_pk_bf16_f32 v4, v140, v141
	v_cvt_pk_bf16_f32 v5, v136, v137
	v_mov_b32_e32 v6, 0
	global_store_dwordx4 v[138:139], v[2:5], off offset:256 sc1
	v_mov_b32_e32 v7, v6
	v_mov_b32_e32 v8, v6
	v_mov_b32_e32 v9, v6
	v_mov_b32_e32 v2, v6
	v_mov_b32_e32 v3, v6
	v_mov_b32_e32 v4, v6
	v_mov_b32_e32 v5, v6
	s_and_b64 vcc, exec, s[36:37]
	s_mov_b64 s[0:1], -1
	s_cbranch_vccnz .LBB0_252
